# v34: v26 + P6 x-row prefetch a full iteration ahead + loop-head SALU sunk behind ph1 loads (4 GEMM loops) + attention counter/compare above the loop-back barrier
# speedup vs baseline: 1.0056x; 1.0051x over previous
; #define PG8_STAGE(bufoff, gbase, voff) do { _Pragma("unroll") for (int _i = 0; _i < 2; ++_i) \
;         __builtin_amdgcn_global_load_lds((const unsigned*)((const char*)(gbase) + (voff)[_i]), (LAS unsigned*)(lds + (bufoff) + ldsw + _i * 8192), 16, 0, 0); } while (0)
; #define PG8_LDA(dst, b, h) do { _Pragma("unroll") for (int m = 0; m < 4; ++m) _Pragma("unroll") for (int k = 0; k < 2; ++k) dst[m][k] = *(const LAS bf16x8*)(lds + PG8_SA(b, h) + aoff + m * 2048 + k * 1024); } while (0)
; #define PG8_LDB(dst, b, h) do { _Pragma("unroll") for (int n = 0; n < 2; ++n) _Pragma("unroll") for (int k = 0; k < 2; ++k) dst[n][k] = *(const LAS bf16x8*)(lds + PG8_SB(b, h) + boff + n * 2048 + k * 1024); } while (0)
; #define PG8_MMA(ai, bj, At, Bt) do { __builtin_amdgcn_s_setprio(1); _Pragma("unroll") for (int m = 0; m < 4; ++m) _Pragma("unroll") for (int n = 0; n < 2; ++n) _Pragma("unroll") for (int k = 0; k < 2; ++k) \
;         acc[ai][bj][m][n] = __builtin_amdgcn_mfma_f32_16x16x32_bf16(Bt[n][k], At[m][k], acc[ai][bj][m][n], 0, 0, 0); __builtin_amdgcn_s_setprio(0); } while (0)
; #define PG8_WAIT_V(n) asm volatile("s_waitcnt vmcnt(" #n ")" ::: "memory")
; #define PG8_WAIT_L(n) asm volatile("s_waitcnt lgkmcnt(" #n ")" ::: "memory")
; #define PG8_BAR __builtin_amdgcn_s_barrier()
; template <class Epi, class Sched, bool ALIGN_EPI, bool SP2>
; __device__ __forceinline__ void gemm_phase(LAS unsigned char* lds, const Gemm g, const Sched& S, const Epi& E) {
;     ...
;         for (int t = 0; t < nt; t += 2) {
;             const bool last = (t == nt - 2);
;             const char* a1 = cA + (size_t)(t + 1) * kstep;
;             const char* a2 = last ? nA : cA + (size_t)(t + 2) * kstep; const char* b2 = last ? nB : cB + (size_t)(t + 2) * kstep;
;             const char* a3 = a2 + kstep; const char* b3 = b2 + kstep;
;             if constexpr (SP2) {
;             PG8_LDB(B0, 0, 0); PG8_LDB(B1, 0, 1); PG8_SCHED; PG8_LDA(At, 0, 0); PG8_STAGE(PG8_SA(1, 1), a1 + hstep, voffA);
;             PG8_WAIT_V(8); PG8_WAIT_L(0); PG8_BAR; PG8_MMA(0, 0, At, B0); PG8_MMA(0, 1, At, B1); PG8_BAR; PG8_SCHED;
;             PG8_LDA(At, 0, 1); PG8_STAGE(PG8_SB(0, 0), b2, voffB); PG8_STAGE(PG8_SB(0, 1), b2 + hstep, voffB); PG8_STAGE(PG8_SA(0, 0), a2, voffA);
;             PG8_WAIT_V(8); PG8_WAIT_L(0); PG8_BAR; PG8_MMA(1, 0, At, B0); PG8_MMA(1, 1, At, B1); PG8_BAR; PG8_SCHED;
.LBB0_216:
	s_add_i32 m0, s71, 0xc000
	s_nop 0
	global_load_lds_dwordx4 v160, s[6:7]
	s_add_i32 m0, s71, 0xe000
	s_nop 0
	global_load_lds_dwordx4 v162, s[6:7]
	ds_read_b128 v[128:131], v177
	ds_read_b128 v[132:135], v177 offset:1024
	ds_read_b128 v[136:139], v177 offset:2048
	ds_read_b128 v[140:143], v177 offset:3072
	ds_read_b128 v[168:171], v178
	ds_read_b128 v[184:187], v178 offset:1024
	ds_read_b128 v[188:191], v178 offset:2048
	ds_read_b128 v[192:195], v178 offset:3072
	ds_read_b128 v[196:199], v179
	ds_read_b128 v[200:203], v179 offset:1024
	ds_read_b128 v[204:207], v179 offset:2048
	ds_read_b128 v[208:211], v179 offset:3072
	ds_read_b128 v[212:215], v179 offset:4096
	ds_read_b128 v[216:219], v179 offset:5120
	ds_read_b128 v[220:223], v179 offset:6144
	ds_read_b128 v[224:227], v179 offset:7168
	s_add_u32 s8, s6, 0xfffc0080
	s_addc_u32 s9, s7, -1
	s_cmp_eq_u32 s43, 12
	s_cselect_b32 s11, s2, s9
	s_cselect_b32 s10, s3, s8
	s_cselect_b32 s9, s5, s42
	s_cselect_b32 s8, s12, s13
	s_waitcnt vmcnt(8)
	s_waitcnt lgkmcnt(0)
	s_barrier
	s_setprio 1
	s_waitcnt lgkmcnt(0)
	v_mfma_f32_16x16x32_bf16 v[124:127], v[128:131], v[196:199], v[124:127]
	v_mfma_f32_16x16x32_bf16 v[120:123], v[136:139], v[196:199], v[120:123]
	v_mfma_f32_16x16x32_bf16 v[116:119], v[128:131], v[204:207], v[116:119]
	v_mfma_f32_16x16x32_bf16 v[112:115], v[136:139], v[204:207], v[112:115]
	v_mfma_f32_16x16x32_bf16 v[108:111], v[128:131], v[212:215], v[108:111]
	v_mfma_f32_16x16x32_bf16 v[104:107], v[136:139], v[212:215], v[104:107]
	v_mfma_f32_16x16x32_bf16 v[100:103], v[128:131], v[220:223], v[100:103]
	v_mfma_f32_16x16x32_bf16 v[96:99], v[136:139], v[220:223], v[96:99]
	v_mfma_f32_16x16x32_bf16 v[124:127], v[132:135], v[200:203], v[124:127]
	v_mfma_f32_16x16x32_bf16 v[120:123], v[140:143], v[200:203], v[120:123]
	v_mfma_f32_16x16x32_bf16 v[116:119], v[132:135], v[208:211], v[116:119]
	v_mfma_f32_16x16x32_bf16 v[112:115], v[140:143], v[208:211], v[112:115]
	v_mfma_f32_16x16x32_bf16 v[108:111], v[132:135], v[216:219], v[108:111]
	v_mfma_f32_16x16x32_bf16 v[104:107], v[140:143], v[216:219], v[104:107]
	v_mfma_f32_16x16x32_bf16 v[100:103], v[132:135], v[224:227], v[100:103]
	v_mfma_f32_16x16x32_bf16 v[96:99], v[140:143], v[224:227], v[96:99]
	s_setprio 0
	s_setprio 1
	v_mfma_f32_16x16x32_bf16 v[60:63], v[168:171], v[196:199], v[60:63]
	v_mfma_f32_16x16x32_bf16 v[56:59], v[188:191], v[196:199], v[56:59]
	v_mfma_f32_16x16x32_bf16 v[52:55], v[168:171], v[204:207], v[52:55]
	v_mfma_f32_16x16x32_bf16 v[48:51], v[188:191], v[204:207], v[48:51]
	v_mfma_f32_16x16x32_bf16 v[44:47], v[168:171], v[212:215], v[44:47]
	v_mfma_f32_16x16x32_bf16 v[40:43], v[188:191], v[212:215], v[40:43]
	v_mfma_f32_16x16x32_bf16 v[36:39], v[168:171], v[220:223], v[36:39]
	v_mfma_f32_16x16x32_bf16 v[32:35], v[188:191], v[220:223], v[32:35]
	v_mfma_f32_16x16x32_bf16 v[60:63], v[184:187], v[200:203], v[60:63]
	v_mfma_f32_16x16x32_bf16 v[56:59], v[192:195], v[200:203], v[56:59]
	v_mfma_f32_16x16x32_bf16 v[52:55], v[184:187], v[208:211], v[52:55]
	v_mfma_f32_16x16x32_bf16 v[48:51], v[192:195], v[208:211], v[48:51]
	v_mfma_f32_16x16x32_bf16 v[44:47], v[184:187], v[216:219], v[44:47]
	v_mfma_f32_16x16x32_bf16 v[40:43], v[192:195], v[216:219], v[40:43]
	v_mfma_f32_16x16x32_bf16 v[36:39], v[184:187], v[224:227], v[36:39]
	v_mfma_f32_16x16x32_bf16 v[32:35], v[192:195], v[224:227], v[32:35]
	s_setprio 0
	s_barrier
	s_add_i32 s44, s74, s70
	s_mov_b32 m0, s44
	s_nop 0
	global_load_lds_dwordx4 v146, s[8:9]
	s_add_i32 m0, s44, 0x2000
	s_add_u32 s44, s8, 0x40000
	s_addc_u32 s45, s9, 0
	s_add_i32 s50, s75, s70
	global_load_lds_dwordx4 v150, s[8:9]
	s_mov_b32 m0, s50
	s_nop 0
	global_load_lds_dwordx4 v146, s[44:45]
	s_add_i32 m0, s50, 0x2000
	s_nop 0
	global_load_lds_dwordx4 v150, s[44:45]
	s_mov_b32 m0, s71
	s_nop 0
	global_load_lds_dwordx4 v144, s[10:11]
	s_mov_b32 m0, s72
	s_nop 0
	global_load_lds_dwordx4 v148, s[10:11]
	ds_read_b128 v[196:199], v179 offset:16384
	ds_read_b128 v[200:203], v179 offset:17408
	ds_read_b128 v[204:207], v179 offset:18432
	ds_read_b128 v[208:211], v179 offset:19456
	ds_read_b128 v[212:215], v179 offset:20480
	ds_read_b128 v[216:219], v179 offset:21504
	ds_read_b128 v[220:223], v179 offset:22528
	ds_read_b128 v[224:227], v179 offset:23552
	s_waitcnt vmcnt(8)
	s_waitcnt lgkmcnt(0)
	s_barrier
	s_setprio 1
	s_waitcnt lgkmcnt(0)
	v_mfma_f32_16x16x32_bf16 v[92:95], v[128:131], v[196:199], v[92:95]
	v_mfma_f32_16x16x32_bf16 v[88:91], v[136:139], v[196:199], v[88:91]
	v_mfma_f32_16x16x32_bf16 v[84:87], v[128:131], v[204:207], v[84:87]
	v_mfma_f32_16x16x32_bf16 v[80:83], v[136:139], v[204:207], v[80:83]
	v_mfma_f32_16x16x32_bf16 v[76:79], v[128:131], v[212:215], v[76:79]
	v_mfma_f32_16x16x32_bf16 v[72:75], v[136:139], v[212:215], v[72:75]
	v_mfma_f32_16x16x32_bf16 v[68:71], v[128:131], v[220:223], v[68:71]
	v_mfma_f32_16x16x32_bf16 v[64:67], v[136:139], v[220:223], v[64:67]
	v_mfma_f32_16x16x32_bf16 v[92:95], v[132:135], v[200:203], v[92:95]
	v_mfma_f32_16x16x32_bf16 v[88:91], v[140:143], v[200:203], v[88:91]
	v_mfma_f32_16x16x32_bf16 v[84:87], v[132:135], v[208:211], v[84:87]
	v_mfma_f32_16x16x32_bf16 v[80:83], v[140:143], v[208:211], v[80:83]
	v_mfma_f32_16x16x32_bf16 v[76:79], v[132:135], v[216:219], v[76:79]
	v_mfma_f32_16x16x32_bf16 v[72:75], v[140:143], v[216:219], v[72:75]
	v_mfma_f32_16x16x32_bf16 v[68:71], v[132:135], v[224:227], v[68:71]
	v_mfma_f32_16x16x32_bf16 v[64:67], v[140:143], v[224:227], v[64:67]
	s_setprio 0
	s_setprio 1
	v_mfma_f32_16x16x32_bf16 v[28:31], v[168:171], v[196:199], v[28:31]
	v_mfma_f32_16x16x32_bf16 v[24:27], v[188:191], v[196:199], v[24:27]
	v_mfma_f32_16x16x32_bf16 v[20:23], v[168:171], v[204:207], v[20:23]
	v_mfma_f32_16x16x32_bf16 v[16:19], v[188:191], v[204:207], v[16:19]
	v_mfma_f32_16x16x32_bf16 v[12:15], v[168:171], v[212:215], v[12:15]
	v_mfma_f32_16x16x32_bf16 v[8:11], v[188:191], v[212:215], v[8:11]
	v_mfma_f32_16x16x32_bf16 v[4:7], v[168:171], v[220:223], v[4:7]
	v_mfma_f32_16x16x32_bf16 v[0:3], v[188:191], v[220:223], v[0:3]
	v_mfma_f32_16x16x32_bf16 v[28:31], v[184:187], v[200:203], v[28:31]
	v_mfma_f32_16x16x32_bf16 v[24:27], v[192:195], v[200:203], v[24:27]
	v_mfma_f32_16x16x32_bf16 v[20:23], v[184:187], v[208:211], v[20:23]
	v_mfma_f32_16x16x32_bf16 v[16:19], v[192:195], v[208:211], v[16:19]
	v_mfma_f32_16x16x32_bf16 v[12:15], v[184:187], v[216:219], v[12:15]
	v_mfma_f32_16x16x32_bf16 v[8:11], v[192:195], v[216:219], v[8:11]
	v_mfma_f32_16x16x32_bf16 v[4:7], v[184:187], v[224:227], v[4:7]
	v_mfma_f32_16x16x32_bf16 v[0:3], v[192:195], v[224:227], v[0:3]
	s_setprio 0
	s_barrier
; #define PG8_STAGE(bufoff, gbase, voff) do { _Pragma("unroll") for (int _i = 0; _i < 2; ++_i) \
;         __builtin_amdgcn_global_load_lds((const unsigned*)((const char*)(gbase) + (voff)[_i]), (LAS unsigned*)(lds + (bufoff) + ldsw + _i * 8192), 16, 0, 0); } while (0)
; #define PG8_LDA(dst, b, h) do { _Pragma("unroll") for (int m = 0; m < 4; ++m) _Pragma("unroll") for (int k = 0; k < 2; ++k) dst[m][k] = *(const LAS bf16x8*)(lds + PG8_SA(b, h) + aoff + m * 2048 + k * 1024); } while (0)
; #define PG8_LDB(dst, b, h) do { _Pragma("unroll") for (int n = 0; n < 2; ++n) _Pragma("unroll") for (int k = 0; k < 2; ++k) dst[n][k] = *(const LAS bf16x8*)(lds + PG8_SB(b, h) + boff + n * 2048 + k * 1024); } while (0)
; #define PG8_MMA(ai, bj, At, Bt) do { __builtin_amdgcn_s_setprio(1); _Pragma("unroll") for (int m = 0; m < 4; ++m) _Pragma("unroll") for (int n = 0; n < 2; ++n) _Pragma("unroll") for (int k = 0; k < 2; ++k) \
;         acc[ai][bj][m][n] = __builtin_amdgcn_mfma_f32_16x16x32_bf16(Bt[n][k], At[m][k], acc[ai][bj][m][n], 0, 0, 0); __builtin_amdgcn_s_setprio(0); } while (0)
; #define PG8_WAIT_V(n) asm volatile("s_waitcnt vmcnt(" #n ")" ::: "memory")
; #define PG8_WAIT_L(n) asm volatile("s_waitcnt lgkmcnt(" #n ")" ::: "memory")
; #define PG8_BAR __builtin_amdgcn_s_barrier()
; #define PG8_SCHED __builtin_amdgcn_sched_barrier(0)
; template <class Epi, class Sched, bool ALIGN_EPI, bool SP2>
; __device__ __forceinline__ void gemm_phase(LAS unsigned char* lds, const Gemm g, const Sched& S, const Epi& E) {
;     ...
;             PG8_LDB(B0, 1, 0); PG8_LDB(B1, 1, 1); PG8_SCHED; PG8_LDA(At, 1, 0); PG8_STAGE(PG8_SA(0, 1), a2 + hstep, voffA);
;             PG8_WAIT_V(8); PG8_WAIT_L(0); PG8_BAR; PG8_MMA(0, 0, At, B0); PG8_MMA(0, 1, At, B1); PG8_BAR; PG8_SCHED;
;             PG8_LDA(At, 1, 1); PG8_STAGE(PG8_SB(1, 0), b3, voffB); PG8_STAGE(PG8_SB(1, 1), b3 + hstep, voffB); PG8_STAGE(PG8_SA(1, 0), a3, voffA);
;             PG8_WAIT_V(8); PG8_WAIT_L(0); PG8_BAR; PG8_MMA(1, 0, At, B0); PG8_MMA(1, 1, At, B1); PG8_BAR; PG8_SCHED;
;     ...
;         }
;         if constexpr (ALIGN_EPI) { if (wr == 0) PG8_BAR; }
	s_add_i32 s44, 0, 0x18000
	s_add_i32 s45, 0, 0x1c000
	v_add_u32_e32 v140, s44, v174
	v_add_u32_e32 v152, s45, v174
	s_add_u32 s10, s10, 0x40000
	s_addc_u32 s11, s11, 0
	s_mov_b32 m0, s73
	s_nop 0
	global_load_lds_dwordx4 v144, s[10:11]
	s_mov_b32 m0, s82
	s_nop 0
	global_load_lds_dwordx4 v148, s[10:11]
	ds_read_b128 v[128:131], v140
	ds_read_b128 v[132:135], v140 offset:1024
	ds_read_b128 v[136:139], v140 offset:2048
	ds_read_b128 v[140:143], v140 offset:3072
	ds_read_b128 v[168:171], v152
	ds_read_b128 v[184:187], v152 offset:1024
	ds_read_b128 v[188:191], v152 offset:2048
	ds_read_b128 v[192:195], v152 offset:3072
	ds_read_b128 v[196:199], v179 offset:32768
	ds_read_b128 v[200:203], v179 offset:33792
	ds_read_b128 v[204:207], v179 offset:34816
	ds_read_b128 v[208:211], v179 offset:35840
	ds_read_b128 v[212:215], v179 offset:36864
	ds_read_b128 v[216:219], v179 offset:37888
	ds_read_b128 v[220:223], v179 offset:38912
	ds_read_b128 v[224:227], v179 offset:39936
	s_waitcnt vmcnt(8)
	s_waitcnt lgkmcnt(0)
	s_barrier
	s_setprio 1
	s_waitcnt lgkmcnt(0)
	v_mfma_f32_16x16x32_bf16 v[124:127], v[128:131], v[196:199], v[124:127]
	v_mfma_f32_16x16x32_bf16 v[120:123], v[136:139], v[196:199], v[120:123]
	v_mfma_f32_16x16x32_bf16 v[116:119], v[128:131], v[204:207], v[116:119]
	v_mfma_f32_16x16x32_bf16 v[112:115], v[136:139], v[204:207], v[112:115]
	v_mfma_f32_16x16x32_bf16 v[108:111], v[128:131], v[212:215], v[108:111]
	v_mfma_f32_16x16x32_bf16 v[104:107], v[136:139], v[212:215], v[104:107]
	v_mfma_f32_16x16x32_bf16 v[100:103], v[128:131], v[220:223], v[100:103]
	v_mfma_f32_16x16x32_bf16 v[96:99], v[136:139], v[220:223], v[96:99]
	v_mfma_f32_16x16x32_bf16 v[124:127], v[132:135], v[200:203], v[124:127]
	v_mfma_f32_16x16x32_bf16 v[120:123], v[140:143], v[200:203], v[120:123]
	v_mfma_f32_16x16x32_bf16 v[116:119], v[132:135], v[208:211], v[116:119]
	v_mfma_f32_16x16x32_bf16 v[112:115], v[140:143], v[208:211], v[112:115]
	v_mfma_f32_16x16x32_bf16 v[108:111], v[132:135], v[216:219], v[108:111]
	v_mfma_f32_16x16x32_bf16 v[104:107], v[140:143], v[216:219], v[104:107]
	v_mfma_f32_16x16x32_bf16 v[100:103], v[132:135], v[224:227], v[100:103]
	v_mfma_f32_16x16x32_bf16 v[96:99], v[140:143], v[224:227], v[96:99]
	s_setprio 0
	s_setprio 1
	v_mfma_f32_16x16x32_bf16 v[60:63], v[168:171], v[196:199], v[60:63]
	v_mfma_f32_16x16x32_bf16 v[56:59], v[188:191], v[196:199], v[56:59]
	v_mfma_f32_16x16x32_bf16 v[52:55], v[168:171], v[204:207], v[52:55]
	v_mfma_f32_16x16x32_bf16 v[48:51], v[188:191], v[204:207], v[48:51]
	v_mfma_f32_16x16x32_bf16 v[44:47], v[168:171], v[212:215], v[44:47]
	v_mfma_f32_16x16x32_bf16 v[40:43], v[188:191], v[212:215], v[40:43]
	v_mfma_f32_16x16x32_bf16 v[36:39], v[168:171], v[220:223], v[36:39]
	v_mfma_f32_16x16x32_bf16 v[32:35], v[188:191], v[220:223], v[32:35]
	v_mfma_f32_16x16x32_bf16 v[60:63], v[184:187], v[200:203], v[60:63]
	v_mfma_f32_16x16x32_bf16 v[56:59], v[192:195], v[200:203], v[56:59]
	v_mfma_f32_16x16x32_bf16 v[52:55], v[184:187], v[208:211], v[52:55]
	v_mfma_f32_16x16x32_bf16 v[48:51], v[192:195], v[208:211], v[48:51]
	v_mfma_f32_16x16x32_bf16 v[44:47], v[184:187], v[216:219], v[44:47]
	v_mfma_f32_16x16x32_bf16 v[40:43], v[192:195], v[216:219], v[40:43]
	v_mfma_f32_16x16x32_bf16 v[36:39], v[184:187], v[224:227], v[36:39]
	v_mfma_f32_16x16x32_bf16 v[32:35], v[192:195], v[224:227], v[32:35]
	s_setprio 0
	s_barrier
	s_add_u32 s100, s10, 0xfffc0080
	s_addc_u32 s101, s11, -1
	s_add_u32 s98, s8, 0x80
	s_addc_u32 s99, s9, 0
	s_add_i32 s10, s44, s70
	s_mov_b32 m0, s10
	s_nop 0
	global_load_lds_dwordx4 v146, s[98:99]
	s_add_i32 m0, s10, 0x2000
	s_add_u32 s8, s8, 0x40080
	s_addc_u32 s9, s9, 0
	s_add_i32 s10, s45, s70
	global_load_lds_dwordx4 v150, s[98:99]
	s_mov_b32 m0, s10
	s_nop 0
	global_load_lds_dwordx4 v146, s[8:9]
	s_add_i32 m0, s10, 0x2000
	s_nop 0
	global_load_lds_dwordx4 v150, s[8:9]
	s_mov_b32 m0, s83
	s_nop 0
	global_load_lds_dwordx4 v144, s[100:101]
	s_mov_b32 m0, s84
	s_nop 0
	global_load_lds_dwordx4 v148, s[100:101]
	ds_read_b128 v[196:199], v179 offset:49152
	ds_read_b128 v[200:203], v179 offset:50176
	ds_read_b128 v[204:207], v179 offset:51200
	ds_read_b128 v[208:211], v179 offset:52224
	ds_read_b128 v[212:215], v179 offset:53248
	ds_read_b128 v[216:219], v179 offset:54272
	ds_read_b128 v[220:223], v179 offset:55296
	ds_read_b128 v[224:227], v179 offset:56320
	s_waitcnt vmcnt(8)
	s_waitcnt lgkmcnt(0)
	s_barrier
	s_setprio 1
	s_waitcnt lgkmcnt(0)
	v_mfma_f32_16x16x32_bf16 v[92:95], v[128:131], v[196:199], v[92:95]
	v_mfma_f32_16x16x32_bf16 v[88:91], v[136:139], v[196:199], v[88:91]
	v_mfma_f32_16x16x32_bf16 v[84:87], v[128:131], v[204:207], v[84:87]
	v_mfma_f32_16x16x32_bf16 v[80:83], v[136:139], v[204:207], v[80:83]
	v_mfma_f32_16x16x32_bf16 v[76:79], v[128:131], v[212:215], v[76:79]
	v_mfma_f32_16x16x32_bf16 v[72:75], v[136:139], v[212:215], v[72:75]
	v_mfma_f32_16x16x32_bf16 v[68:71], v[128:131], v[220:223], v[68:71]
	v_mfma_f32_16x16x32_bf16 v[64:67], v[136:139], v[220:223], v[64:67]
	v_mfma_f32_16x16x32_bf16 v[92:95], v[132:135], v[200:203], v[92:95]
	v_mfma_f32_16x16x32_bf16 v[88:91], v[140:143], v[200:203], v[88:91]
	v_mfma_f32_16x16x32_bf16 v[84:87], v[132:135], v[208:211], v[84:87]
	v_mfma_f32_16x16x32_bf16 v[80:83], v[140:143], v[208:211], v[80:83]
	v_mfma_f32_16x16x32_bf16 v[76:79], v[132:135], v[216:219], v[76:79]
	v_mfma_f32_16x16x32_bf16 v[72:75], v[140:143], v[216:219], v[72:75]
	v_mfma_f32_16x16x32_bf16 v[68:71], v[132:135], v[224:227], v[68:71]
	v_mfma_f32_16x16x32_bf16 v[64:67], v[140:143], v[224:227], v[64:67]
	s_setprio 0
	s_setprio 1
	v_mfma_f32_16x16x32_bf16 v[28:31], v[168:171], v[196:199], v[28:31]
	v_mfma_f32_16x16x32_bf16 v[24:27], v[188:191], v[196:199], v[24:27]
	v_mfma_f32_16x16x32_bf16 v[20:23], v[168:171], v[204:207], v[20:23]
	v_mfma_f32_16x16x32_bf16 v[16:19], v[188:191], v[204:207], v[16:19]
	v_mfma_f32_16x16x32_bf16 v[12:15], v[168:171], v[212:215], v[12:15]
	v_mfma_f32_16x16x32_bf16 v[8:11], v[188:191], v[212:215], v[8:11]
	v_mfma_f32_16x16x32_bf16 v[4:7], v[168:171], v[220:223], v[4:7]
	v_mfma_f32_16x16x32_bf16 v[0:3], v[188:191], v[220:223], v[0:3]
	v_mfma_f32_16x16x32_bf16 v[28:31], v[184:187], v[200:203], v[28:31]
	v_mfma_f32_16x16x32_bf16 v[24:27], v[192:195], v[200:203], v[24:27]
	v_mfma_f32_16x16x32_bf16 v[20:23], v[184:187], v[208:211], v[20:23]
	v_mfma_f32_16x16x32_bf16 v[16:19], v[192:195], v[208:211], v[16:19]
	v_mfma_f32_16x16x32_bf16 v[12:15], v[184:187], v[216:219], v[12:15]
	v_mfma_f32_16x16x32_bf16 v[8:11], v[192:195], v[216:219], v[8:11]
	v_mfma_f32_16x16x32_bf16 v[4:7], v[184:187], v[224:227], v[4:7]
	v_mfma_f32_16x16x32_bf16 v[0:3], v[192:195], v[224:227], v[0:3]
	s_setprio 0
	s_barrier
	s_add_i32 s43, s43, 2
	s_add_u32 s6, s6, 0x100
	s_addc_u32 s7, s7, 0
	s_add_u32 s13, s13, 0x100
	s_addc_u32 s42, s42, 0
	s_cmp_gt_u32 s43, 13
	s_cbranch_scc0 .LBB0_216
	s_and_b64 vcc, exec, s[34:35]
	s_cbranch_vccnz .LBB0_221
	v_lshl_add_u32 v168, s4, 8, v155
	s_cmp_lg_u32 s16, 2
	s_mov_b64 s[4:5], -1
	s_cbranch_scc1 .LBB0_222

; #define LAS __attribute__((address_space(3)))
; #define AT_SB() __builtin_amdgcn_sched_barrier(0)
; #define AT_KLD(KB) do { _Pragma("unroll") for (int s_ = 0; s_ < 4; ++s_) { kf[2 * s_] = *(const LAS bf16x8*)((KB) + foff[s_]); kf[2 * s_ + 1] = *(const LAS bf16x8*)((KB) + 4096 + foff[s_]); } } while (0)
; #define AT_QK(S0, S1) do { _Pragma("unroll") for (int i_ = 0; i_ < 16; ++i_) { S0[i_] = 0.f; S1[i_] = 0.f; } \
;         _Pragma("unroll") for (int s_ = 0; s_ < 4; ++s_) { S0 = __builtin_amdgcn_mfma_f32_32x32x16_bf16(kf[2 * s_], qf[s_], S0, 0, 0, 0); \
;             S1 = __builtin_amdgcn_mfma_f32_32x32x16_bf16(kf[2 * s_ + 1], qf[s_], S1, 0, 0, 0); } } while (0)
; #define AT_PV(VF, PF) do { _Pragma("unroll") for (int dt_ = 0; dt_ < 4; ++dt_) o[dt_] = __builtin_amdgcn_mfma_f32_32x32x16_bf16(VF[dt_], PF, o[dt_], 0, 0, 0); } while (0)
; #define AT_VLD(VF, VB, KS) do { _Pragma("unroll") for (int dt_ = 0; dt_ < 4; ++dt_) VF[dt_] = *(const LAS bf16x8*)((VB) + dt_ * 4096 + foff[KS]); } while (0)
; __device__ __forceinline__ void attn_unit(LAS unsigned char* lds, const bf16_t* __restrict__ DQ, const bf16_t* __restrict__ DK, const bf16_t* __restrict__ VT,
;                                           bf16_t* __restrict__ OD, const float* __restrict__ g_out, float lam, int b, int h, int qb) {
;     ...
;     for (int j = 0; j < NP - 1; ++j) {
;         const int st0 = (j & 1) * 2, sn = ((j + 1) & 1) * 2;
;         const LAS unsigned char* kb0 = lds + st0 * STB + map * 8192; const LAS unsigned char* vb0 = lds + st0 * STB + ST_V;
;         const LAS unsigned char* kb1 = kb0 + STB; const LAS unsigned char* vb1 = vb0 + STB;
;         f32x16 a0, a1, b0, b1;
;         AT_DMA(2 * j + 2, sn); AT_KLD(kb0); AT_VLD(vfa, vb0, 0); AT_PV(vfb, pfn); AT_SB();
;         AT_QK(a0, a1); AT_SB();
;         AT_DMA(2 * j + 3, sn + 1); AT_KLD(kb1); AT_SB();
;         AT_QK(b0, b1); AT_EXPBLK(a0, 0, pfc); AT_SB();
;         AT_VLD(vfb, vb0, 1); AT_PV(vfa, pfc); AT_EXPBLK(a0, 8, pfn); AT_SB();
;         AT_VLD(vfa, vb0, 2); AT_PV(vfb, pfn); AT_EXPBLK(a1, 0, pfc); AT_SB();
.LBB0_369:
	s_and_b32 s9, s6, 0x10000
	s_add_i32 s48, s8, -1
	s_lshl_b64 s[16:17], s[48:49], 16
	s_add_u32 s16, s16, s98
	s_addc_u32 s17, s17, s99
	s_add_i32 s22, s1, s9
	s_lshl_b64 s[18:19], s[48:49], 7
	s_add_u32 s18, s18, s100
	s_addc_u32 s19, s19, s101
	s_add_i32 s9, s22, 0x4000
	s_mov_b32 m0, s22
	s_waitcnt lgkmcnt(0)
	v_mfma_f32_32x32x16_bf16 v[48:63], v[84:87], v[72:75], v[48:63]
	global_load_lds_dwordx4 v150, s[16:17]
	s_mov_b32 m0, s9
	s_add_i32 s9, s6, 0xffff0000
	global_load_lds_dwordx4 v154, s[18:19]
	s_add_i32 m0, s22, 0x400
	s_and_b32 s9, s9, 0x10000
	global_load_lds_dwordx4 v152, s[16:17]
	s_add_i32 m0, s22, 0x4400
	s_add_i32 s16, s9, 0
	global_load_lds_dwordx4 v156, s[18:19]
	s_add_i32 s9, s16, s5
	v_add_u32_e32 v148, s9, v168
	v_mfma_f32_32x32x16_bf16 v[32:47], v[80:83], v[72:75], v[32:47]
	v_add_u32_e32 v169, s9, v167
	v_add_u32_e32 v174, s9, v166
	v_add_u32_e32 v200, s9, v165
	v_add_u32_e32 v208, s16, v168
	ds_read_b128 v[76:79], v148
	ds_read_b128 v[84:87], v148 offset:4096
	ds_read_b128 v[80:83], v169
	ds_read_b128 v[88:91], v169 offset:4096
	ds_read_b128 v[92:95], v174
	ds_read_b128 v[112:115], v174 offset:4096
	v_mfma_f32_32x32x16_bf16 v[16:31], v[68:71], v[72:75], v[16:31]
	ds_read_b128 v[68:71], v200
	ds_read_b128 v[116:119], v200 offset:4096
	ds_read_b128 v[170:173], v208 offset:16384
	ds_read_b128 v[176:179], v208 offset:20480
	ds_read_b128 v[180:183], v208 offset:24576
	ds_read_b128 v[184:187], v208 offset:28672
	v_mfma_f32_32x32x16_bf16 v[0:15], v[64:67], v[72:75], v[0:15]
	s_waitcnt lgkmcnt(0)
	v_mfma_f32_32x32x16_bf16 v[96:111], v[84:87], v[140:143], 0
	v_mfma_f32_32x32x16_bf16 v[96:111], v[88:91], v[136:139], v[96:111]
	v_mfma_f32_32x32x16_bf16 v[96:111], v[112:115], v[132:135], v[96:111]
	v_mfma_f32_32x32x16_bf16 v[96:111], v[116:119], v[128:131], v[96:111]
	s_mov_b32 s9, s49
	s_lshl_b64 s[18:19], s[8:9], 16
	s_add_u32 s18, s18, s98
	s_addc_u32 s19, s19, s99
	s_add_i32 m0, s22, 0x8000
	s_lshl_b64 s[20:21], s[8:9], 7
	s_add_u32 s20, s20, s100
	s_addc_u32 s21, s21, s101
	s_add_i32 s9, s22, 0xc000
	global_load_lds_dwordx4 v150, s[18:19]
	s_mov_b32 m0, s9
	v_mfma_f32_32x32x16_bf16 v[112:127], v[76:79], v[140:143], 0
	global_load_lds_dwordx4 v154, s[20:21]
	s_add_i32 m0, s22, 0x8400
	s_nop 0
	global_load_lds_dwordx4 v152, s[18:19]
	s_add_i32 m0, s22, 0xc400
	v_mfma_f32_32x32x16_bf16 v[112:127], v[80:83], v[136:139], v[112:127]
	global_load_lds_dwordx4 v156, s[20:21]
	v_mfma_f32_32x32x16_bf16 v[112:127], v[92:95], v[132:135], v[112:127]
	ds_read_b128 v[80:83], v148 offset:32768
	ds_read_b128 v[64:67], v148 offset:36864
	ds_read_b128 v[188:191], v169 offset:32768
	ds_read_b128 v[84:87], v169 offset:36864
	ds_read_b128 v[192:195], v174 offset:32768
	ds_read_b128 v[88:91], v174 offset:36864
	ds_read_b128 v[196:199], v200 offset:32768
	ds_read_b128 v[92:95], v200 offset:36864
	v_mfma_f32_32x32x16_bf16 v[112:127], v[68:71], v[128:131], v[112:127]
	s_waitcnt lgkmcnt(0)
	v_mfma_f32_32x32x16_bf16 v[64:79], v[64:67], v[140:143], 0
	s_nop 9
	v_exp_f32_e32 v112, v112
	v_mfma_f32_32x32x16_bf16 v[64:79], v[84:87], v[136:139], v[64:79]
	v_mfma_f32_32x32x16_bf16 v[64:79], v[88:91], v[132:135], v[64:79]
	v_mfma_f32_32x32x16_bf16 v[64:79], v[92:95], v[128:131], v[64:79]
	v_mfma_f32_32x32x16_bf16 v[80:95], v[80:83], v[140:143], 0
	v_mfma_f32_32x32x16_bf16 v[80:95], v[188:191], v[136:139], v[80:95]
	v_exp_f32_e32 v188, v113
	v_exp_f32_e32 v113, v114
	v_exp_f32_e32 v189, v115
	v_exp_f32_e32 v114, v116
	v_exp_f32_e32 v116, v117
	v_exp_f32_e32 v115, v118
	v_exp_f32_e32 v117, v119
	v_mfma_f32_32x32x16_bf16 v[80:95], v[192:195], v[132:135], v[80:95]
	v_add_f32_e64 v118, v112, v188
	v_add_f32_e64 v119, v113, v189
	v_cvt_pk_bf16_f32 v112, v112, v188
	v_add_f32_e64 v200, v118, v118
	v_add_f32_e64 v201, v118, v119
	v_pk_add_f32 v[118:119], v[114:115], v[116:117]
	v_cvt_pk_bf16_f32 v113, v113, v189
	v_pk_add_f32 v[202:203], v[118:119], v[118:119] op_sel_hi:[0,1]
	v_cvt_pk_bf16_f32 v114, v114, v116
	v_mfma_f32_32x32x16_bf16 v[80:95], v[196:199], v[128:131], v[80:95]
	v_cvt_pk_bf16_f32 v115, v115, v117
	s_nop 1
	v_mfma_f32_32x32x16_bf16 v[48:63], v[170:173], v[112:115], v[48:63]
	v_add_u32_e32 v169, s16, v167
	ds_read_b128 v[116:119], v169 offset:16384
	ds_read_b128 v[170:173], v169 offset:20480
	ds_read_b128 v[188:191], v169 offset:24576
	ds_read_b128 v[192:195], v169 offset:28672
	v_exp_f32_e32 v120, v120
	v_exp_f32_e32 v121, v121
	v_exp_f32_e32 v122, v122
	v_exp_f32_e32 v123, v123
	v_exp_f32_e32 v124, v124
	v_mfma_f32_32x32x16_bf16 v[32:47], v[176:179], v[112:115], v[32:47]
	v_exp_f32_e32 v125, v125
	v_exp_f32_e32 v126, v126
	v_exp_f32_e32 v127, v127
	v_add_f32_e32 v197, v120, v121
	v_add_f32_e32 v199, v122, v123
	v_add_f32_e32 v205, v124, v125
	v_add_f32_e32 v207, v126, v127
	v_mfma_f32_32x32x16_bf16 v[16:31], v[180:183], v[112:115], v[16:31]
	v_cvt_pk_bf16_f32 v120, v120, v121
	v_cvt_pk_bf16_f32 v121, v122, v123
	v_cvt_pk_bf16_f32 v122, v124, v125
	v_cvt_pk_bf16_f32 v123, v126, v127
	v_mfma_f32_32x32x16_bf16 v[0:15], v[184:187], v[112:115], v[0:15]
	s_waitcnt lgkmcnt(0)
	v_mfma_f32_32x32x16_bf16 v[48:63], v[116:119], v[120:123], v[48:63]
	v_add_u32_e32 v174, s16, v166
	ds_read_b128 v[112:115], v174 offset:16384
	ds_read_b128 v[116:119], v174 offset:20480
	v_exp_f32_e32 v196, v96
	v_exp_f32_e32 v198, v97
	v_exp_f32_e32 v204, v98
	v_exp_f32_e32 v98, v100
	v_exp_f32_e32 v100, v101
	v_mfma_f32_32x32x16_bf16 v[32:47], v[170:173], v[120:123], v[32:47]
	ds_read_b128 v[124:127], v174 offset:24576
	ds_read_b128 v[170:173], v174 offset:28672
	v_exp_f32_e32 v206, v99
	v_exp_f32_e32 v200, v102
	v_exp_f32_e32 v202, v103
	v_add_f32_e32 v148, v98, v100
	v_cvt_pk_bf16_f32 v96, v196, v198
	v_cvt_pk_bf16_f32 v97, v204, v206
	v_mfma_f32_32x32x16_bf16 v[16:31], v[188:191], v[120:123], v[16:31]
	v_cvt_pk_bf16_f32 v98, v98, v100
	v_cvt_pk_bf16_f32 v99, v200, v202
	v_mfma_f32_32x32x16_bf16 v[0:15], v[192:195], v[120:123], v[0:15]
	v_add_u32_e32 v186, s16, v165
	s_waitcnt lgkmcnt(0)
; #define AT_SB() __builtin_amdgcn_sched_barrier(0)
; #define AT_PV(VF, PF) do { _Pragma("unroll") for (int dt_ = 0; dt_ < 4; ++dt_) o[dt_] = __builtin_amdgcn_mfma_f32_32x32x16_bf16(VF[dt_], PF, o[dt_], 0, 0, 0); } while (0)
; #define AT_VLD(VF, VB, KS) do { _Pragma("unroll") for (int dt_ = 0; dt_ < 4; ++dt_) VF[dt_] = *(const LAS bf16x8*)((VB) + dt_ * 4096 + foff[KS]); } while (0)
; __device__ __forceinline__ void attn_unit(LAS unsigned char* lds, const bf16_t* __restrict__ DQ, const bf16_t* __restrict__ DK, const bf16_t* __restrict__ VT,
;                                           bf16_t* __restrict__ OD, const float* __restrict__ g_out, float lam, int b, int h, int qb) {
;     ...
;         AT_VLD(vfa, vb0, 2); AT_PV(vfb, pfn); AT_EXPBLK(a1, 0, pfc); AT_SB();
;         AT_VLD(vfb, vb0, 3); AT_PV(vfa, pfc); AT_EXPBLK(a1, 8, pfn); AT_SB();
;         AT_VLD(vfa, vb1, 0); AT_PV(vfb, pfn); AT_EXPBLK(b0, 0, pfc); AT_SB();
;         AT_VLD(vfb, vb1, 1); AT_PV(vfa, pfc); AT_EXPBLK(b0, 8, pfn); AT_SB();
;         AT_VLD(vfa, vb1, 2); AT_PV(vfb, pfn); AT_EXPBLK(b1, 0, pfc); AT_SB();
;         AT_VLD(vfb, vb1, 3); AT_PV(vfa, pfc); AT_EXPBLK(b1, 8, pfn); AT_SB();
;         asm volatile("s_waitcnt vmcnt(0)" ::: "memory");
;         __builtin_amdgcn_s_barrier(); asm volatile("" ::: "memory");
;     }
	v_mfma_f32_32x32x16_bf16 v[48:63], v[112:115], v[96:99], v[48:63]
	v_add_f32_e64 v112, v196, v198
	v_add_f32_e64 v113, v197, v199
	v_add_f32_e64 v114, v204, v206
	v_add_f32_e64 v115, v205, v207
	ds_read_b128 v[100:103], v186 offset:16384
	ds_read_b128 v[120:123], v186 offset:20480
	ds_read_b128 v[176:179], v186 offset:24576
	ds_read_b128 v[180:183], v186 offset:28672
	v_pk_add_f32 v[112:113], v[112:113], v[114:115]
	v_pk_add_f32 v[114:115], v[200:201], v[202:203]
	v_exp_f32_e32 v184, v105
	v_pk_add_f32 v[114:115], v[148:149], v[114:115]
	v_mfma_f32_32x32x16_bf16 v[32:47], v[116:119], v[96:99], v[32:47]
	v_exp_f32_e32 v148, v104
	v_exp_f32_e32 v106, v106
	v_exp_f32_e32 v116, v107
	v_exp_f32_e32 v149, v108
	v_exp_f32_e32 v185, v109
	v_exp_f32_e32 v107, v110
	v_exp_f32_e32 v117, v111
	v_mfma_f32_32x32x16_bf16 v[16:31], v[124:127], v[96:99], v[16:31]
	v_add_f32_e64 v104, v148, v184
	v_add_f32_e64 v105, v149, v185
	v_add_f32_e64 v118, v112, v114
	v_add_f32_e64 v119, v113, v115
	v_add_f32_e64 v108, v106, v116
	v_add_f32_e64 v109, v107, v117
	v_cvt_pk_bf16_f32 v107, v107, v117
	v_pk_add_f32 v[104:105], v[104:105], v[108:109]
	s_nop 0
	v_pk_add_f32 v[124:125], v[104:105], v[104:105] op_sel_hi:[0,1]
	v_mfma_f32_32x32x16_bf16 v[0:15], v[170:173], v[96:99], v[0:15]
	v_cvt_pk_bf16_f32 v104, v148, v184
	v_cvt_pk_bf16_f32 v105, v106, v116
	v_cvt_pk_bf16_f32 v106, v149, v185
	s_waitcnt lgkmcnt(0)
	s_nop 0
	v_mfma_f32_32x32x16_bf16 v[48:63], v[100:103], v[104:107], v[48:63]
	ds_read_b128 v[96:99], v208 offset:49152
	ds_read_b128 v[100:103], v208 offset:53248
	ds_read_b128 v[108:111], v208 offset:57344
	ds_read_b128 v[112:115], v208 offset:61440
	v_exp_f32_e32 v80, v80
	v_exp_f32_e32 v116, v81
	v_exp_f32_e32 v81, v82
	v_exp_f32_e32 v117, v83
	v_exp_f32_e32 v82, v84
	v_exp_f32_e32 v84, v85
	v_mfma_f32_32x32x16_bf16 v[32:47], v[120:123], v[104:107], v[32:47]
	v_exp_f32_e32 v83, v86
	v_exp_f32_e32 v85, v87
	v_pk_add_f32 v[86:87], v[80:81], v[116:117]
	v_cvt_pk_bf16_f32 v80, v80, v116
	v_pk_add_f32 v[120:121], v[86:87], v[86:87] op_sel_hi:[0,1]
	v_pk_add_f32 v[86:87], v[82:83], v[84:85]
	v_cvt_pk_bf16_f32 v81, v81, v117
	v_mfma_f32_32x32x16_bf16 v[16:31], v[176:179], v[104:107], v[16:31]
	v_cvt_pk_bf16_f32 v82, v82, v84
	v_cvt_pk_bf16_f32 v83, v83, v85
	v_add_f32_e64 v126, v118, v118
	v_add_f32_e64 v127, v118, v119
	v_add_f32_e64 v122, v86, v86
	v_add_f32_e64 v123, v86, v87
	v_mfma_f32_32x32x16_bf16 v[0:15], v[180:183], v[104:107], v[0:15]
	s_waitcnt lgkmcnt(0)
	v_mfma_f32_32x32x16_bf16 v[48:63], v[96:99], v[80:83], v[48:63]
	ds_read_b128 v[84:87], v169 offset:49152
	ds_read_b128 v[96:99], v169 offset:53248
	ds_read_b128 v[104:107], v169 offset:57344
	ds_read_b128 v[116:119], v169 offset:61440
	v_exp_f32_e32 v88, v88
	v_exp_f32_e32 v89, v89
	v_exp_f32_e32 v90, v90
	v_exp_f32_e32 v91, v91
	v_exp_f32_e32 v92, v92
	v_exp_f32_e32 v93, v93
	v_mfma_f32_32x32x16_bf16 v[32:47], v[100:103], v[80:83], v[32:47]
	v_exp_f32_e32 v94, v94
	v_exp_f32_e32 v95, v95
	v_add_f32_e32 v149, v88, v89
	v_add_f32_e32 v171, v90, v91
	v_add_f32_e32 v173, v92, v93
	v_add_f32_e32 v177, v94, v95
	v_cvt_pk_bf16_f32 v88, v88, v89
	v_mfma_f32_32x32x16_bf16 v[16:31], v[108:111], v[80:83], v[16:31]
	v_cvt_pk_bf16_f32 v89, v90, v91
	v_cvt_pk_bf16_f32 v90, v92, v93
	v_cvt_pk_bf16_f32 v91, v94, v95
	v_mfma_f32_32x32x16_bf16 v[0:15], v[112:115], v[80:83], v[0:15]
	s_waitcnt lgkmcnt(0)
	v_mfma_f32_32x32x16_bf16 v[48:63], v[84:87], v[88:91], v[48:63]
	v_exp_f32_e32 v148, v64
	v_exp_f32_e32 v170, v65
	v_exp_f32_e32 v172, v66
	v_exp_f32_e32 v176, v67
	v_exp_f32_e32 v124, v68
	v_exp_f32_e32 v126, v69
	v_exp_f32_e32 v120, v70
	v_mfma_f32_32x32x16_bf16 v[32:47], v[96:99], v[88:91], v[32:47]
	ds_read_b128 v[92:95], v174 offset:49152
	ds_read_b128 v[96:99], v174 offset:53248
	ds_read_b128 v[100:103], v174 offset:57344
	ds_read_b128 v[108:111], v174 offset:61440
	v_exp_f32_e32 v122, v71
	v_mfma_f32_32x32x16_bf16 v[16:31], v[104:107], v[88:91], v[16:31]
	v_cvt_pk_bf16_f32 v104, v148, v170
	v_cvt_pk_bf16_f32 v105, v172, v176
	v_cvt_pk_bf16_f32 v106, v124, v126
	v_cvt_pk_bf16_f32 v107, v120, v122
	v_mfma_f32_32x32x16_bf16 v[0:15], v[116:119], v[88:91], v[0:15]
	v_add_f32_e64 v88, v148, v170
	v_add_f32_e64 v89, v149, v171
	v_add_f32_e64 v90, v172, v176
	v_add_f32_e64 v91, v173, v177
	s_waitcnt lgkmcnt(0)
	v_mfma_f32_32x32x16_bf16 v[48:63], v[92:95], v[104:107], v[48:63]
	v_add_f32_e64 v88, v88, v90
	v_add_f32_e64 v89, v89, v91
	v_add_f32_e64 v90, v124, v126
	v_add_f32_e64 v91, v125, v127
	v_add_f32_e64 v92, v120, v122
	v_add_f32_e64 v93, v121, v123
	v_exp_f32_e32 v94, v73
	v_pk_add_f32 v[90:91], v[90:91], v[92:93]
	v_exp_f32_e32 v92, v72
	v_exp_f32_e32 v74, v74
	v_mfma_f32_32x32x16_bf16 v[32:47], v[96:99], v[104:107], v[32:47]
	v_exp_f32_e32 v96, v75
	v_exp_f32_e32 v93, v76
	v_exp_f32_e32 v95, v77
	v_exp_f32_e32 v75, v78
	v_exp_f32_e32 v97, v79
	ds_read_b128 v[84:87], v186 offset:49152
	ds_read_b128 v[80:83], v186 offset:53248
	ds_read_b128 v[68:71], v186 offset:57344
	ds_read_b128 v[64:67], v186 offset:61440
	v_pk_add_f32 v[76:77], v[92:93], v[94:95]
	v_mfma_f32_32x32x16_bf16 v[16:31], v[100:103], v[104:107], v[16:31]
	v_add_f32_e64 v78, v74, v96
	v_add_f32_e64 v79, v75, v97
	v_add_f32_e64 v72, v88, v90
	v_add_f32_e64 v73, v89, v91
	v_add_f32_e64 v76, v76, v78
	v_add_f32_e64 v77, v77, v79
	v_add_f32_e32 v72, v72, v73
	v_add_f32_e32 v73, v76, v77
	v_add_f32_e32 v149, v73, v72
	v_cvt_pk_bf16_f32 v72, v92, v94
	v_mfma_f32_32x32x16_bf16 v[0:15], v[108:111], v[104:107], v[0:15]
	v_cvt_pk_bf16_f32 v73, v74, v96
	v_cvt_pk_bf16_f32 v74, v93, v95
	v_cvt_pk_bf16_f32 v75, v75, v97
	s_waitcnt vmcnt(0)
	s_add_i32 s8, s8, 2
	s_add_i32 s15, s15, -1
	s_add_i32 s6, s6, 0x10000
	s_cmp_eq_u32 s15, 0
	s_barrier
	s_cbranch_scc0 .LBB0_369
	s_branch .LBB0_371

; #define PG8_STAGE(bufoff, gbase, voff) do { _Pragma("unroll") for (int _i = 0; _i < 2; ++_i) \
;         __builtin_amdgcn_global_load_lds((const unsigned*)((const char*)(gbase) + (voff)[_i]), (LAS unsigned*)(lds + (bufoff) + ldsw + _i * 8192), 16, 0, 0); } while (0)
; #define PG8_LDA(dst, b, h) do { _Pragma("unroll") for (int m = 0; m < 4; ++m) _Pragma("unroll") for (int k = 0; k < 2; ++k) dst[m][k] = *(const LAS bf16x8*)(lds + PG8_SA(b, h) + aoff + m * 2048 + k * 1024); } while (0)
; #define PG8_LDB(dst, b, h) do { _Pragma("unroll") for (int n = 0; n < 2; ++n) _Pragma("unroll") for (int k = 0; k < 2; ++k) dst[n][k] = *(const LAS bf16x8*)(lds + PG8_SB(b, h) + boff + n * 2048 + k * 1024); } while (0)
; #define PG8_MMA(ai, bj, At, Bt) do { __builtin_amdgcn_s_setprio(1); _Pragma("unroll") for (int m = 0; m < 4; ++m) _Pragma("unroll") for (int n = 0; n < 2; ++n) _Pragma("unroll") for (int k = 0; k < 2; ++k) \
;         acc[ai][bj][m][n] = __builtin_amdgcn_mfma_f32_16x16x32_bf16(Bt[n][k], At[m][k], acc[ai][bj][m][n], 0, 0, 0); __builtin_amdgcn_s_setprio(0); } while (0)
; #define PG8_WAIT_V(n) asm volatile("s_waitcnt vmcnt(" #n ")" ::: "memory")
; #define PG8_WAIT_L(n) asm volatile("s_waitcnt lgkmcnt(" #n ")" ::: "memory")
; #define PG8_BAR __builtin_amdgcn_s_barrier()
; template <class Epi, class Sched, bool ALIGN_EPI, bool SP2>
; __device__ __forceinline__ void gemm_phase(LAS unsigned char* lds, const Gemm g, const Sched& S, const Epi& E) {
;     ...
;         for (int t = 0; t < nt; t += 2) {
;             const bool last = (t == nt - 2);
;             const char* a1 = cA + (size_t)(t + 1) * kstep;
;             const char* a2 = last ? nA : cA + (size_t)(t + 2) * kstep; const char* b2 = last ? nB : cB + (size_t)(t + 2) * kstep;
;             const char* a3 = a2 + kstep; const char* b3 = b2 + kstep;
;             if constexpr (SP2) {
;             PG8_LDB(B0, 0, 0); PG8_LDB(B1, 0, 1); PG8_SCHED; PG8_LDA(At, 0, 0); PG8_STAGE(PG8_SA(1, 1), a1 + hstep, voffA);
;             PG8_WAIT_V(8); PG8_WAIT_L(0); PG8_BAR; PG8_MMA(0, 0, At, B0); PG8_MMA(0, 1, At, B1); PG8_BAR; PG8_SCHED;
;             PG8_LDA(At, 0, 1); PG8_STAGE(PG8_SB(0, 0), b2, voffB); PG8_STAGE(PG8_SB(0, 1), b2 + hstep, voffB); PG8_STAGE(PG8_SA(0, 0), a2, voffA);
;             PG8_WAIT_V(8); PG8_WAIT_L(0); PG8_BAR; PG8_MMA(1, 0, At, B0); PG8_MMA(1, 1, At, B1); PG8_BAR; PG8_SCHED;
.LBB0_468:
	v_add_u32_e32 v140, s62, v187
	v_add_u32_e32 v156, s63, v187
	s_add_i32 m0, s43, 0xc000
	s_nop 0
	global_load_lds_dwordx4 v176, s[28:29]
	s_add_i32 m0, s43, 0xe000
	s_nop 0
	global_load_lds_dwordx4 v178, s[28:29]
	ds_read_b128 v[128:131], v140
	ds_read_b128 v[132:135], v140 offset:1024
	ds_read_b128 v[136:139], v140 offset:2048
	ds_read_b128 v[140:143], v140 offset:3072
	ds_read_b128 v[144:147], v156
	ds_read_b128 v[148:151], v156 offset:1024
	ds_read_b128 v[152:155], v156 offset:2048
	ds_read_b128 v[156:159], v156 offset:3072
	ds_read_b128 v[160:163], v188
	ds_read_b128 v[190:193], v188 offset:1024
	ds_read_b128 v[194:197], v188 offset:2048
	ds_read_b128 v[198:201], v188 offset:3072
	ds_read_b128 v[202:205], v188 offset:4096
	ds_read_b128 v[206:209], v188 offset:5120
	ds_read_b128 v[210:213], v188 offset:6144
	ds_read_b128 v[214:217], v188 offset:7168
	s_add_u32 s34, s28, 0xfffe0080
	s_addc_u32 s35, s29, -1
	s_cmp_eq_u32 s58, 4
	s_cselect_b32 s37, s21, s35
	s_cselect_b32 s36, s50, s34
	s_cselect_b32 s35, s23, s57
	s_cselect_b32 s34, s51, s56
	s_waitcnt vmcnt(8)
	s_waitcnt lgkmcnt(0)
	s_barrier
	s_setprio 1
	s_waitcnt lgkmcnt(0)
	v_mfma_f32_16x16x32_bf16 v[124:127], v[128:131], v[160:163], v[124:127]
	v_mfma_f32_16x16x32_bf16 v[120:123], v[136:139], v[160:163], v[120:123]
	v_mfma_f32_16x16x32_bf16 v[116:119], v[128:131], v[194:197], v[116:119]
	v_mfma_f32_16x16x32_bf16 v[112:115], v[136:139], v[194:197], v[112:115]
	v_mfma_f32_16x16x32_bf16 v[108:111], v[128:131], v[202:205], v[108:111]
	v_mfma_f32_16x16x32_bf16 v[104:107], v[136:139], v[202:205], v[104:107]
	v_mfma_f32_16x16x32_bf16 v[100:103], v[128:131], v[210:213], v[100:103]
	v_mfma_f32_16x16x32_bf16 v[96:99], v[136:139], v[210:213], v[96:99]
	v_mfma_f32_16x16x32_bf16 v[124:127], v[132:135], v[190:193], v[124:127]
	v_mfma_f32_16x16x32_bf16 v[120:123], v[140:143], v[190:193], v[120:123]
	v_mfma_f32_16x16x32_bf16 v[116:119], v[132:135], v[198:201], v[116:119]
	v_mfma_f32_16x16x32_bf16 v[112:115], v[140:143], v[198:201], v[112:115]
	v_mfma_f32_16x16x32_bf16 v[108:111], v[132:135], v[206:209], v[108:111]
	v_mfma_f32_16x16x32_bf16 v[104:107], v[140:143], v[206:209], v[104:107]
	v_mfma_f32_16x16x32_bf16 v[100:103], v[132:135], v[214:217], v[100:103]
	v_mfma_f32_16x16x32_bf16 v[96:99], v[140:143], v[214:217], v[96:99]
	s_setprio 0
	s_setprio 1
	v_mfma_f32_16x16x32_bf16 v[92:95], v[144:147], v[160:163], v[92:95]
	v_mfma_f32_16x16x32_bf16 v[88:91], v[152:155], v[160:163], v[88:91]
	v_mfma_f32_16x16x32_bf16 v[84:87], v[144:147], v[194:197], v[84:87]
	v_mfma_f32_16x16x32_bf16 v[80:83], v[152:155], v[194:197], v[80:83]
	v_mfma_f32_16x16x32_bf16 v[76:79], v[144:147], v[202:205], v[76:79]
	v_mfma_f32_16x16x32_bf16 v[72:75], v[152:155], v[202:205], v[72:75]
	v_mfma_f32_16x16x32_bf16 v[68:71], v[144:147], v[210:213], v[68:71]
	v_mfma_f32_16x16x32_bf16 v[64:67], v[152:155], v[210:213], v[64:67]
	v_mfma_f32_16x16x32_bf16 v[92:95], v[148:151], v[190:193], v[92:95]
	v_mfma_f32_16x16x32_bf16 v[88:91], v[156:159], v[190:193], v[88:91]
	v_mfma_f32_16x16x32_bf16 v[84:87], v[148:151], v[198:201], v[84:87]
	v_mfma_f32_16x16x32_bf16 v[80:83], v[156:159], v[198:201], v[80:83]
	v_mfma_f32_16x16x32_bf16 v[76:79], v[148:151], v[206:209], v[76:79]
	v_mfma_f32_16x16x32_bf16 v[72:75], v[156:159], v[206:209], v[72:75]
	v_mfma_f32_16x16x32_bf16 v[68:71], v[148:151], v[214:217], v[68:71]
	v_mfma_f32_16x16x32_bf16 v[64:67], v[156:159], v[214:217], v[64:67]
	s_setprio 0
	s_barrier
	s_add_i32 s59, s62, s42
	s_mov_b32 m0, s59
	s_nop 0
	global_load_lds_dwordx4 v166, s[34:35]
	s_add_i32 m0, s59, 0x2000
	s_add_u32 s72, s34, 0x20000
	s_addc_u32 s73, s35, 0
	s_add_i32 s59, s63, s42
	global_load_lds_dwordx4 v170, s[34:35]
	s_mov_b32 m0, s59
	s_nop 0
	global_load_lds_dwordx4 v166, s[72:73]
	s_add_i32 m0, s59, 0x2000
	s_nop 0
	global_load_lds_dwordx4 v170, s[72:73]
	s_mov_b32 m0, s43
	s_nop 0
	global_load_lds_dwordx4 v164, s[36:37]
	s_mov_b32 m0, s44
	s_nop 0
	global_load_lds_dwordx4 v168, s[36:37]
	ds_read_b128 v[160:163], v188 offset:16384
	ds_read_b128 v[190:193], v188 offset:17408
	ds_read_b128 v[194:197], v188 offset:18432
	ds_read_b128 v[198:201], v188 offset:19456
	ds_read_b128 v[202:205], v188 offset:20480
	ds_read_b128 v[206:209], v188 offset:21504
	ds_read_b128 v[210:213], v188 offset:22528
	ds_read_b128 v[214:217], v188 offset:23552
	s_waitcnt vmcnt(8)
	s_waitcnt lgkmcnt(0)
	s_barrier
	s_setprio 1
	s_waitcnt lgkmcnt(0)
	v_mfma_f32_16x16x32_bf16 v[60:63], v[128:131], v[160:163], v[60:63]
	v_mfma_f32_16x16x32_bf16 v[56:59], v[136:139], v[160:163], v[56:59]
	v_mfma_f32_16x16x32_bf16 v[52:55], v[128:131], v[194:197], v[52:55]
	v_mfma_f32_16x16x32_bf16 v[48:51], v[136:139], v[194:197], v[48:51]
	v_mfma_f32_16x16x32_bf16 v[44:47], v[128:131], v[202:205], v[44:47]
	v_mfma_f32_16x16x32_bf16 v[40:43], v[136:139], v[202:205], v[40:43]
	v_mfma_f32_16x16x32_bf16 v[36:39], v[128:131], v[210:213], v[36:39]
	v_mfma_f32_16x16x32_bf16 v[32:35], v[136:139], v[210:213], v[32:35]
	v_mfma_f32_16x16x32_bf16 v[60:63], v[132:135], v[190:193], v[60:63]
	v_mfma_f32_16x16x32_bf16 v[56:59], v[140:143], v[190:193], v[56:59]
	v_mfma_f32_16x16x32_bf16 v[52:55], v[132:135], v[198:201], v[52:55]
	v_mfma_f32_16x16x32_bf16 v[48:51], v[140:143], v[198:201], v[48:51]
	v_mfma_f32_16x16x32_bf16 v[44:47], v[132:135], v[206:209], v[44:47]
	v_mfma_f32_16x16x32_bf16 v[40:43], v[140:143], v[206:209], v[40:43]
	v_mfma_f32_16x16x32_bf16 v[36:39], v[132:135], v[214:217], v[36:39]
	v_mfma_f32_16x16x32_bf16 v[32:35], v[140:143], v[214:217], v[32:35]
	s_setprio 0
	s_setprio 1
	v_mfma_f32_16x16x32_bf16 v[28:31], v[144:147], v[160:163], v[28:31]
	v_mfma_f32_16x16x32_bf16 v[24:27], v[152:155], v[160:163], v[24:27]
	v_mfma_f32_16x16x32_bf16 v[20:23], v[144:147], v[194:197], v[20:23]
	v_mfma_f32_16x16x32_bf16 v[16:19], v[152:155], v[194:197], v[16:19]
	v_mfma_f32_16x16x32_bf16 v[12:15], v[144:147], v[202:205], v[12:15]
	v_mfma_f32_16x16x32_bf16 v[8:11], v[152:155], v[202:205], v[8:11]
	v_mfma_f32_16x16x32_bf16 v[4:7], v[144:147], v[210:213], v[4:7]
	v_mfma_f32_16x16x32_bf16 v[0:3], v[152:155], v[210:213], v[0:3]
	v_mfma_f32_16x16x32_bf16 v[28:31], v[148:151], v[190:193], v[28:31]
	v_mfma_f32_16x16x32_bf16 v[24:27], v[156:159], v[190:193], v[24:27]
	v_mfma_f32_16x16x32_bf16 v[20:23], v[148:151], v[198:201], v[20:23]
	v_mfma_f32_16x16x32_bf16 v[16:19], v[156:159], v[198:201], v[16:19]
	v_mfma_f32_16x16x32_bf16 v[12:15], v[148:151], v[206:209], v[12:15]
	v_mfma_f32_16x16x32_bf16 v[8:11], v[156:159], v[206:209], v[8:11]
	v_mfma_f32_16x16x32_bf16 v[4:7], v[148:151], v[214:217], v[4:7]
	v_mfma_f32_16x16x32_bf16 v[0:3], v[156:159], v[214:217], v[0:3]
	s_setprio 0
	s_barrier
; #define PG8_STAGE(bufoff, gbase, voff) do { _Pragma("unroll") for (int _i = 0; _i < 2; ++_i) \
;         __builtin_amdgcn_global_load_lds((const unsigned*)((const char*)(gbase) + (voff)[_i]), (LAS unsigned*)(lds + (bufoff) + ldsw + _i * 8192), 16, 0, 0); } while (0)
; #define PG8_LDA(dst, b, h) do { _Pragma("unroll") for (int m = 0; m < 4; ++m) _Pragma("unroll") for (int k = 0; k < 2; ++k) dst[m][k] = *(const LAS bf16x8*)(lds + PG8_SA(b, h) + aoff + m * 2048 + k * 1024); } while (0)
; #define PG8_LDB(dst, b, h) do { _Pragma("unroll") for (int n = 0; n < 2; ++n) _Pragma("unroll") for (int k = 0; k < 2; ++k) dst[n][k] = *(const LAS bf16x8*)(lds + PG8_SB(b, h) + boff + n * 2048 + k * 1024); } while (0)
; #define PG8_MMA(ai, bj, At, Bt) do { __builtin_amdgcn_s_setprio(1); _Pragma("unroll") for (int m = 0; m < 4; ++m) _Pragma("unroll") for (int n = 0; n < 2; ++n) _Pragma("unroll") for (int k = 0; k < 2; ++k) \
;         acc[ai][bj][m][n] = __builtin_amdgcn_mfma_f32_16x16x32_bf16(Bt[n][k], At[m][k], acc[ai][bj][m][n], 0, 0, 0); __builtin_amdgcn_s_setprio(0); } while (0)
; #define PG8_WAIT_V(n) asm volatile("s_waitcnt vmcnt(" #n ")" ::: "memory")
; #define PG8_WAIT_L(n) asm volatile("s_waitcnt lgkmcnt(" #n ")" ::: "memory")
; #define PG8_BAR __builtin_amdgcn_s_barrier()
; #define PG8_SCHED __builtin_amdgcn_sched_barrier(0)
; template <class Epi, class Sched, bool ALIGN_EPI, bool SP2>
; __device__ __forceinline__ void gemm_phase(LAS unsigned char* lds, const Gemm g, const Sched& S, const Epi& E) {
;     ...
;             PG8_LDB(B0, 1, 0); PG8_LDB(B1, 1, 1); PG8_SCHED; PG8_LDA(At, 1, 0); PG8_STAGE(PG8_SA(0, 1), a2 + hstep, voffA);
;             PG8_WAIT_V(8); PG8_WAIT_L(0); PG8_BAR; PG8_MMA(0, 0, At, B0); PG8_MMA(0, 1, At, B1); PG8_BAR; PG8_SCHED;
;             PG8_LDA(At, 1, 1); PG8_STAGE(PG8_SB(1, 0), b3, voffB); PG8_STAGE(PG8_SB(1, 1), b3 + hstep, voffB); PG8_STAGE(PG8_SA(1, 0), a3, voffA);
;             PG8_WAIT_V(8); PG8_WAIT_L(0); PG8_BAR; PG8_MMA(1, 0, At, B0); PG8_MMA(1, 1, At, B1); PG8_BAR; PG8_SCHED;
;     ...
;         }
;         if constexpr (ALIGN_EPI) { if (wr == 0) PG8_BAR; }
	s_add_i32 s59, 0, 0x18000
	s_add_i32 s71, 0, 0x1c000
	v_add_u32_e32 v140, s59, v187
	v_add_u32_e32 v156, s71, v187
	s_add_u32 s36, s36, 0x20000
	s_addc_u32 s37, s37, 0
	s_mov_b32 m0, s45
	s_nop 0
	global_load_lds_dwordx4 v164, s[36:37]
	s_mov_b32 m0, s46
	s_nop 0
	global_load_lds_dwordx4 v168, s[36:37]
	ds_read_b128 v[128:131], v140
	ds_read_b128 v[132:135], v140 offset:1024
	ds_read_b128 v[136:139], v140 offset:2048
	ds_read_b128 v[140:143], v140 offset:3072
	ds_read_b128 v[144:147], v156
	ds_read_b128 v[148:151], v156 offset:1024
	ds_read_b128 v[152:155], v156 offset:2048
	ds_read_b128 v[156:159], v156 offset:3072
	ds_read_b128 v[160:163], v188 offset:32768
	ds_read_b128 v[190:193], v188 offset:33792
	ds_read_b128 v[194:197], v188 offset:34816
	ds_read_b128 v[198:201], v188 offset:35840
	ds_read_b128 v[202:205], v188 offset:36864
	ds_read_b128 v[206:209], v188 offset:37888
	ds_read_b128 v[210:213], v188 offset:38912
	ds_read_b128 v[214:217], v188 offset:39936
	s_waitcnt vmcnt(8)
	s_waitcnt lgkmcnt(0)
	s_barrier
	s_setprio 1
	s_waitcnt lgkmcnt(0)
	v_mfma_f32_16x16x32_bf16 v[124:127], v[128:131], v[160:163], v[124:127]
	v_mfma_f32_16x16x32_bf16 v[120:123], v[136:139], v[160:163], v[120:123]
	v_mfma_f32_16x16x32_bf16 v[116:119], v[128:131], v[194:197], v[116:119]
	v_mfma_f32_16x16x32_bf16 v[112:115], v[136:139], v[194:197], v[112:115]
	v_mfma_f32_16x16x32_bf16 v[108:111], v[128:131], v[202:205], v[108:111]
	v_mfma_f32_16x16x32_bf16 v[104:107], v[136:139], v[202:205], v[104:107]
	v_mfma_f32_16x16x32_bf16 v[100:103], v[128:131], v[210:213], v[100:103]
	v_mfma_f32_16x16x32_bf16 v[96:99], v[136:139], v[210:213], v[96:99]
	v_mfma_f32_16x16x32_bf16 v[124:127], v[132:135], v[190:193], v[124:127]
	v_mfma_f32_16x16x32_bf16 v[120:123], v[140:143], v[190:193], v[120:123]
	v_mfma_f32_16x16x32_bf16 v[116:119], v[132:135], v[198:201], v[116:119]
	v_mfma_f32_16x16x32_bf16 v[112:115], v[140:143], v[198:201], v[112:115]
	v_mfma_f32_16x16x32_bf16 v[108:111], v[132:135], v[206:209], v[108:111]
	v_mfma_f32_16x16x32_bf16 v[104:107], v[140:143], v[206:209], v[104:107]
	v_mfma_f32_16x16x32_bf16 v[100:103], v[132:135], v[214:217], v[100:103]
	v_mfma_f32_16x16x32_bf16 v[96:99], v[140:143], v[214:217], v[96:99]
	s_setprio 0
	s_setprio 1
	v_mfma_f32_16x16x32_bf16 v[92:95], v[144:147], v[160:163], v[92:95]
	v_mfma_f32_16x16x32_bf16 v[88:91], v[152:155], v[160:163], v[88:91]
	v_mfma_f32_16x16x32_bf16 v[84:87], v[144:147], v[194:197], v[84:87]
	v_mfma_f32_16x16x32_bf16 v[80:83], v[152:155], v[194:197], v[80:83]
	v_mfma_f32_16x16x32_bf16 v[76:79], v[144:147], v[202:205], v[76:79]
	v_mfma_f32_16x16x32_bf16 v[72:75], v[152:155], v[202:205], v[72:75]
	v_mfma_f32_16x16x32_bf16 v[68:71], v[144:147], v[210:213], v[68:71]
	v_mfma_f32_16x16x32_bf16 v[64:67], v[152:155], v[210:213], v[64:67]
	v_mfma_f32_16x16x32_bf16 v[92:95], v[148:151], v[190:193], v[92:95]
	v_mfma_f32_16x16x32_bf16 v[88:91], v[156:159], v[190:193], v[88:91]
	v_mfma_f32_16x16x32_bf16 v[84:87], v[148:151], v[198:201], v[84:87]
	v_mfma_f32_16x16x32_bf16 v[80:83], v[156:159], v[198:201], v[80:83]
	v_mfma_f32_16x16x32_bf16 v[76:79], v[148:151], v[206:209], v[76:79]
	v_mfma_f32_16x16x32_bf16 v[72:75], v[156:159], v[206:209], v[72:75]
	v_mfma_f32_16x16x32_bf16 v[68:71], v[148:151], v[214:217], v[68:71]
	v_mfma_f32_16x16x32_bf16 v[64:67], v[156:159], v[214:217], v[64:67]
	s_setprio 0
	s_barrier
	s_add_u32 s100, s36, 0xfffe0080
	s_addc_u32 s101, s37, -1
	s_add_u32 s98, s34, 0x80
	s_addc_u32 s99, s35, 0
	s_add_i32 s36, s59, s42
	s_mov_b32 m0, s36
	s_nop 0
	global_load_lds_dwordx4 v166, s[98:99]
	s_add_i32 m0, s36, 0x2000
	s_add_u32 s34, s34, 0x20080
	s_addc_u32 s35, s35, 0
	s_add_i32 s36, s71, s42
	global_load_lds_dwordx4 v170, s[98:99]
	s_mov_b32 m0, s36
	s_nop 0
	global_load_lds_dwordx4 v166, s[34:35]
	s_add_i32 m0, s36, 0x2000
	s_nop 0
	global_load_lds_dwordx4 v170, s[34:35]
	s_mov_b32 m0, s54
	s_nop 0
	global_load_lds_dwordx4 v164, s[100:101]
	s_mov_b32 m0, s55
	s_nop 0
	global_load_lds_dwordx4 v168, s[100:101]
	ds_read_b128 v[160:163], v188 offset:49152
	ds_read_b128 v[190:193], v188 offset:50176
	ds_read_b128 v[194:197], v188 offset:51200
	ds_read_b128 v[198:201], v188 offset:52224
	ds_read_b128 v[202:205], v188 offset:53248
	ds_read_b128 v[206:209], v188 offset:54272
	ds_read_b128 v[210:213], v188 offset:55296
	ds_read_b128 v[214:217], v188 offset:56320
	s_waitcnt vmcnt(8)
	s_waitcnt lgkmcnt(0)
	s_barrier
	s_setprio 1
	s_waitcnt lgkmcnt(0)
	v_mfma_f32_16x16x32_bf16 v[60:63], v[128:131], v[160:163], v[60:63]
	v_mfma_f32_16x16x32_bf16 v[56:59], v[136:139], v[160:163], v[56:59]
	v_mfma_f32_16x16x32_bf16 v[52:55], v[128:131], v[194:197], v[52:55]
	v_mfma_f32_16x16x32_bf16 v[48:51], v[136:139], v[194:197], v[48:51]
	v_mfma_f32_16x16x32_bf16 v[44:47], v[128:131], v[202:205], v[44:47]
	v_mfma_f32_16x16x32_bf16 v[40:43], v[136:139], v[202:205], v[40:43]
	v_mfma_f32_16x16x32_bf16 v[36:39], v[128:131], v[210:213], v[36:39]
	v_mfma_f32_16x16x32_bf16 v[32:35], v[136:139], v[210:213], v[32:35]
	v_mfma_f32_16x16x32_bf16 v[60:63], v[132:135], v[190:193], v[60:63]
	v_mfma_f32_16x16x32_bf16 v[56:59], v[140:143], v[190:193], v[56:59]
	v_mfma_f32_16x16x32_bf16 v[52:55], v[132:135], v[198:201], v[52:55]
	v_mfma_f32_16x16x32_bf16 v[48:51], v[140:143], v[198:201], v[48:51]
	v_mfma_f32_16x16x32_bf16 v[44:47], v[132:135], v[206:209], v[44:47]
	v_mfma_f32_16x16x32_bf16 v[40:43], v[140:143], v[206:209], v[40:43]
	v_mfma_f32_16x16x32_bf16 v[36:39], v[132:135], v[214:217], v[36:39]
	v_mfma_f32_16x16x32_bf16 v[32:35], v[140:143], v[214:217], v[32:35]
	s_setprio 0
	s_setprio 1
	v_mfma_f32_16x16x32_bf16 v[28:31], v[144:147], v[160:163], v[28:31]
	v_mfma_f32_16x16x32_bf16 v[24:27], v[152:155], v[160:163], v[24:27]
	v_mfma_f32_16x16x32_bf16 v[20:23], v[144:147], v[194:197], v[20:23]
	v_mfma_f32_16x16x32_bf16 v[16:19], v[152:155], v[194:197], v[16:19]
	v_mfma_f32_16x16x32_bf16 v[12:15], v[144:147], v[202:205], v[12:15]
	v_mfma_f32_16x16x32_bf16 v[8:11], v[152:155], v[202:205], v[8:11]
	v_mfma_f32_16x16x32_bf16 v[4:7], v[144:147], v[210:213], v[4:7]
	v_mfma_f32_16x16x32_bf16 v[0:3], v[152:155], v[210:213], v[0:3]
	v_mfma_f32_16x16x32_bf16 v[28:31], v[148:151], v[190:193], v[28:31]
	v_mfma_f32_16x16x32_bf16 v[24:27], v[156:159], v[190:193], v[24:27]
	v_mfma_f32_16x16x32_bf16 v[20:23], v[148:151], v[198:201], v[20:23]
	v_mfma_f32_16x16x32_bf16 v[16:19], v[156:159], v[198:201], v[16:19]
	v_mfma_f32_16x16x32_bf16 v[12:15], v[148:151], v[206:209], v[12:15]
	v_mfma_f32_16x16x32_bf16 v[8:11], v[156:159], v[206:209], v[8:11]
	v_mfma_f32_16x16x32_bf16 v[4:7], v[148:151], v[214:217], v[4:7]
	v_mfma_f32_16x16x32_bf16 v[0:3], v[156:159], v[214:217], v[0:3]
	s_setprio 0
	s_barrier
	s_add_i32 s58, s58, 2
	s_add_u32 s28, s28, 0x100
	s_addc_u32 s29, s29, 0
	s_add_u32 s56, s56, 0x100
	s_addc_u32 s57, s57, 0
	s_cmp_gt_u32 s58, 5
	s_cbranch_scc0 .LBB0_468
	s_and_b64 vcc, exec, s[18:19]
	s_cbranch_vccz .LBB0_471
	s_barrier

; __device__ __forceinline__ unsigned pk2(float lo, float hi) { f32x2 v = {lo, hi}; bf16x2_t b = __builtin_convertvector(v, bf16x2_t); return __builtin_bit_cast(unsigned, b); }
; __device__ __forceinline__ float bf_lo(unsigned u) { return __uint_as_float(u << 16); }
; __device__ __forceinline__ float bf_hi(unsigned u) { return __uint_as_float(u & 0xffff0000u); }
; __device__ __forceinline__ void norm_rows_bf(const bf16_t* __restrict__ X, const float* __restrict__ g, const float* __restrict__ mod, int sh_off, int sc_off, bf16_t* __restrict__ H, int G) {
;     ...
;     for (int row0 = gw; row0 < MTOK; row0 += 2 * NGW) {
;         u32x4 w[2][2]; float ss[2] = {0.f, 0.f};
; #pragma unroll
;         for (int q = 0; q < 2; ++q) { const int rq = (row0 + q * NGW < MTOK) ? row0 + q * NGW : row0; const u32x4* xr = (const u32x4*)(X + (size_t)rq * DM + 16 * lane);
;             w[q][0] = xr[0]; w[q][1] = xr[1]; }
; #pragma unroll
;         for (int q = 0; q < 2; ++q) { const int row = (row0 + q * NGW < MTOK) ? row0 + q * NGW : row0; const int b = row >> 12;
;             float v[16];
; #pragma unroll
;             for (int e = 0; e < 2; ++e) { v[8 * e] = bf_lo(w[q][e].x); v[8 * e + 1] = bf_hi(w[q][e].x); v[8 * e + 2] = bf_lo(w[q][e].y); v[8 * e + 3] = bf_hi(w[q][e].y);
;                 v[8 * e + 4] = bf_lo(w[q][e].z); v[8 * e + 5] = bf_hi(w[q][e].z); v[8 * e + 6] = bf_lo(w[q][e].w); v[8 * e + 7] = bf_hi(w[q][e].w); }
; #pragma unroll
;             for (int i = 0; i < 16; ++i) ss[q] += v[i] * v[i];
;             const float rn = __builtin_amdgcn_rsqf(wave_sum(ss[q]) * (1.0f / DM) + EPS);
;             const float* mb = mod + (size_t)b * NMOD; const int c = 16 * lane;
;             unsigned o[8];
; #pragma unroll
;             for (int j = 0; j < 4; ++j) { const f32x4 gv = *(const f32x4*)(g + c + 4 * j), sc = *(const f32x4*)(mb + sc_off + c + 4 * j), sh = *(const f32x4*)(mb + sh_off + c + 4 * j);
;                 const f32x4 x = (f32x4){v[4 * j], v[4 * j + 1], v[4 * j + 2], v[4 * j + 3]};
;                 const f32x4 y = x * rn * gv * (sc + 1.0f) + sh; o[2 * j] = pk2(y[0], y[1]); o[2 * j + 1] = pk2(y[2], y[3]); }
;             u32x4* op = (u32x4*)(H + (size_t)row * DM + c);
;             op[0] = (u32x4){o[0], o[1], o[2], o[3]}; op[1] = (u32x4){o[4], o[5], o[6], o[7]}; }
.LBB0_617:
	v_ashrrev_i32_e32 v17, 31, v16
	v_lshlrev_b64 v[64:65], 11, v[16:17]
	v_lshl_add_u64 v[18:19], v[22:23], 0, v[64:65]
	v_ashrrev_i32_e32 v17, 12, v16
	v_mov_b32_e32 v160, v17
	v_mul_hi_i32_i24_e32 v19, 0x6000, v17
	v_mul_i32_i24_e32 v18, 0x6000, v17
	v_lshl_add_u64 v[18:19], s[66:67], 0, v[18:19]
	v_lshl_add_u64 v[66:67], v[18:19], 0, v[20:21]
	v_add_co_u32_e32 v18, vcc, s12, v66
	v_add_u32_e32 v35, s3, v16
	s_nop 0
	v_addc_co_u32_e32 v19, vcc, 0, v67, vcc
	v_cmp_gt_i32_e32 vcc, s2, v35
	global_load_dwordx4 v[44:47], v[18:19], off
	v_lshl_add_u64 v[18:19], v[66:67], 0, s[8:9]
	v_cndmask_b32_e32 v80, v16, v35, vcc
	v_ashrrev_i32_e32 v81, 31, v80
	v_lshlrev_b64 v[26:27], 11, v[80:81]
	v_lshl_add_u64 v[68:69], v[22:23], 0, v[26:27]
	global_load_dwordx4 v[48:51], v[18:19], off offset:32
	global_load_dwordx4 v[52:55], v[18:19], off offset:16
	global_load_dwordx4 v[56:59], v[18:19], off offset:48
	s_nop 0
	v_add_co_u32_e32 v86, vcc, s13, v66
	v_lshl_add_u64 v[82:83], v[24:25], 0, v[64:65]
	s_nop 0
	v_addc_co_u32_e32 v87, vcc, 0, v67, vcc
	v_lshl_add_u64 v[84:85], v[66:67], 0, s[10:11]
	global_load_dwordx4 v[64:67], v[86:87], off
	global_load_dwordx4 v[68:71], v[84:85], off offset:48
	global_load_dwordx4 v[72:75], v[84:85], off offset:32
	global_load_dwordx4 v[76:79], v[84:85], off offset:16
	v_lshl_add_u64 v[26:27], v[24:25], 0, v[26:27]
	s_waitcnt vmcnt(0)
	v_mov_b64_e32 v[36:37], v[104:105]
	v_mov_b64_e32 v[38:39], v[106:107]
	v_mov_b64_e32 v[40:41], v[108:109]
	v_mov_b64_e32 v[42:43], v[110:111]
	v_mov_b64_e32 v[60:61], v[112:113]
	v_mov_b64_e32 v[62:63], v[114:115]
	v_mov_b64_e32 v[16:17], v[116:117]
	v_mov_b64_e32 v[18:19], v[118:119]
	v_mov_b64_e32 v[128:129], v[44:45]
	v_mov_b64_e32 v[130:131], v[46:47]
	v_mov_b64_e32 v[132:133], v[48:49]
	v_mov_b64_e32 v[134:135], v[50:51]
	v_mov_b64_e32 v[136:137], v[52:53]
	v_mov_b64_e32 v[138:139], v[54:55]
	v_mov_b64_e32 v[140:141], v[64:65]
	v_mov_b64_e32 v[142:143], v[66:67]
	v_mov_b64_e32 v[144:145], v[56:57]
	v_mov_b64_e32 v[146:147], v[58:59]
	v_mov_b64_e32 v[148:149], v[76:77]
	v_mov_b64_e32 v[150:151], v[78:79]
	v_mov_b64_e32 v[152:153], v[68:69]
	v_mov_b64_e32 v[154:155], v[70:71]
	v_mov_b64_e32 v[156:157], v[72:73]
	v_mov_b64_e32 v[158:159], v[74:75]
	v_add_u32_e32 v120, s3, v35
	v_min_i32_e32 v120, s14, v120
	v_mov_b32_e32 v121, 0
	v_add_u32_e32 v122, s3, v120
	v_mov_b32_e32 v123, 0
	v_cmp_gt_i32_e32 vcc, s2, v122
	v_lshlrev_b64 v[124:125], 11, v[120:121]
	v_lshl_add_u64 v[126:127], v[22:23], 0, v[124:125]
	v_cndmask_b32_e32 v122, v120, v122, vcc
	global_load_dwordx4 v[104:107], v[126:127], off
	global_load_dwordx4 v[108:111], v[126:127], off offset:16
	v_lshlrev_b64 v[124:125], 11, v[122:123]
	v_lshl_add_u64 v[126:127], v[22:23], 0, v[124:125]
	global_load_dwordx4 v[112:115], v[126:127], off
	global_load_dwordx4 v[116:119], v[126:127], off offset:16
	v_and_b32_e32 v85, 0xffff0000, v36
	v_lshlrev_b32_e32 v84, 16, v36
	v_mul_f32_e32 v81, v85, v85
	v_lshlrev_b32_e32 v36, 16, v37
	v_fmac_f32_e32 v81, v84, v84
	v_and_b32_e32 v37, 0xffff0000, v37
	v_fmac_f32_e32 v81, v36, v36
	v_lshlrev_b32_e32 v86, 16, v38
	v_fmac_f32_e32 v81, v37, v37
	v_and_b32_e32 v87, 0xffff0000, v38
	v_fmac_f32_e32 v81, v86, v86
	v_lshlrev_b32_e32 v38, 16, v39
	v_fmac_f32_e32 v81, v87, v87
	v_and_b32_e32 v39, 0xffff0000, v39
	v_fmac_f32_e32 v81, v38, v38
	v_lshlrev_b32_e32 v88, 16, v40
	v_fmac_f32_e32 v81, v39, v39
	v_and_b32_e32 v89, 0xffff0000, v40
	v_fmac_f32_e32 v81, v88, v88
	v_lshlrev_b32_e32 v40, 16, v41
	v_fmac_f32_e32 v81, v89, v89
	v_and_b32_e32 v41, 0xffff0000, v41
	v_fmac_f32_e32 v81, v40, v40
	v_lshlrev_b32_e32 v90, 16, v42
	v_fmac_f32_e32 v81, v41, v41
	v_and_b32_e32 v91, 0xffff0000, v42
	v_and_b32_e32 v42, 0xffff0000, v43
	v_lshlrev_b32_e32 v43, 16, v43
	v_fmac_f32_e32 v81, v90, v90
	v_pk_mul_f32 v[92:93], v[42:43], v[42:43]
	v_fmac_f32_e32 v81, v91, v91
	v_add_f32_e32 v81, v93, v81
	v_add_f32_e32 v81, v92, v81
	ds_bpermute_b32 v92, v28, v81
	v_lshlrev_b32_e32 v94, 16, v61
	v_and_b32_e32 v95, 0xffff0000, v61
	v_lshlrev_b32_e32 v102, 16, v18
	v_and_b32_e32 v103, 0xffff0000, v18
	s_waitcnt lgkmcnt(0)
	v_add_f32_e32 v81, v81, v92
	ds_bpermute_b32 v93, v29, v81
	v_lshlrev_b32_e32 v92, 16, v60
	v_lshlrev_b32_e32 v96, 16, v62
	v_lshlrev_b32_e32 v98, 16, v63
	v_and_b32_e32 v99, 0xffff0000, v63
	s_waitcnt lgkmcnt(0)
	v_add_f32_e32 v81, v81, v93
	ds_bpermute_b32 v97, v30, v81
	v_and_b32_e32 v93, 0xffff0000, v60
	v_pk_add_f32 v[46:47], v[46:47], 1.0 op_sel_hi:[1,0]
	v_pk_add_f32 v[44:45], v[44:45], 1.0 op_sel_hi:[1,0]
	v_pk_add_f32 v[54:55], v[54:55], 1.0 op_sel_hi:[1,0]
	s_waitcnt lgkmcnt(0)
	v_add_f32_e32 v60, v81, v97
	ds_bpermute_b32 v61, v31, v60
	v_and_b32_e32 v97, 0xffff0000, v62
	v_pk_add_f32 v[52:53], v[52:53], 1.0 op_sel_hi:[1,0]
	v_pk_add_f32 v[50:51], v[50:51], 1.0 op_sel_hi:[1,0]
	v_pk_add_f32 v[48:49], v[48:49], 1.0 op_sel_hi:[1,0]
	s_waitcnt lgkmcnt(0)
	v_add_f32_e32 v60, v60, v61
	ds_bpermute_b32 v61, v32, v60
	v_pk_add_f32 v[58:59], v[58:59], 1.0 op_sel_hi:[1,0]
	v_pk_add_f32 v[56:57], v[56:57], 1.0 op_sel_hi:[1,0]
	v_mul_f32_e32 v81, v93, v93
	v_fmac_f32_e32 v81, v92, v92
	s_waitcnt lgkmcnt(0)
	v_add_f32_e32 v60, v60, v61
	ds_bpermute_b32 v61, v33, v60
	v_fmac_f32_e32 v81, v94, v94
	v_fmac_f32_e32 v81, v95, v95
	v_fmac_f32_e32 v81, v96, v96
	v_fmac_f32_e32 v81, v97, v97
	s_waitcnt lgkmcnt(0)
; __device__ __forceinline__ unsigned pk2(float lo, float hi) { f32x2 v = {lo, hi}; bf16x2_t b = __builtin_convertvector(v, bf16x2_t); return __builtin_bit_cast(unsigned, b); }
; __device__ __forceinline__ float bf_lo(unsigned u) { return __uint_as_float(u << 16); }
; __device__ __forceinline__ float bf_hi(unsigned u) { return __uint_as_float(u & 0xffff0000u); }
; __device__ __forceinline__ void norm_rows_bf(const bf16_t* __restrict__ X, const float* __restrict__ g, const float* __restrict__ mod, int sh_off, int sc_off, bf16_t* __restrict__ H, int G) {
;     ...
;     for (int row0 = gw; row0 < MTOK; row0 += 2 * NGW) {
;         u32x4 w[2][2]; float ss[2] = {0.f, 0.f};
; #pragma unroll
;         for (int q = 0; q < 2; ++q) { const int rq = (row0 + q * NGW < MTOK) ? row0 + q * NGW : row0; const u32x4* xr = (const u32x4*)(X + (size_t)rq * DM + 16 * lane);
;             w[q][0] = xr[0]; w[q][1] = xr[1]; }
; #pragma unroll
;         for (int q = 0; q < 2; ++q) { const int row = (row0 + q * NGW < MTOK) ? row0 + q * NGW : row0; const int b = row >> 12;
;             float v[16];
; #pragma unroll
;             for (int e = 0; e < 2; ++e) { v[8 * e] = bf_lo(w[q][e].x); v[8 * e + 1] = bf_hi(w[q][e].x); v[8 * e + 2] = bf_lo(w[q][e].y); v[8 * e + 3] = bf_hi(w[q][e].y);
;                 v[8 * e + 4] = bf_lo(w[q][e].z); v[8 * e + 5] = bf_hi(w[q][e].z); v[8 * e + 6] = bf_lo(w[q][e].w); v[8 * e + 7] = bf_hi(w[q][e].w); }
; #pragma unroll
;             for (int i = 0; i < 16; ++i) ss[q] += v[i] * v[i];
;             const float rn = __builtin_amdgcn_rsqf(wave_sum(ss[q]) * (1.0f / DM) + EPS);
;             const float* mb = mod + (size_t)b * NMOD; const int c = 16 * lane;
;             unsigned o[8];
; #pragma unroll
;             for (int j = 0; j < 4; ++j) { const f32x4 gv = *(const f32x4*)(g + c + 4 * j), sc = *(const f32x4*)(mb + sc_off + c + 4 * j), sh = *(const f32x4*)(mb + sh_off + c + 4 * j);
;                 const f32x4 x = (f32x4){v[4 * j], v[4 * j + 1], v[4 * j + 2], v[4 * j + 3]};
;                 const f32x4 y = x * rn * gv * (sc + 1.0f) + sh; o[2 * j] = pk2(y[0], y[1]); o[2 * j + 1] = pk2(y[2], y[3]); }
;             u32x4* op = (u32x4*)(H + (size_t)row * DM + c);
;             op[0] = (u32x4){o[0], o[1], o[2], o[3]}; op[1] = (u32x4){o[4], o[5], o[6], o[7]}; }
	v_add_f32_e32 v18, v60, v61
	v_fmamk_f32 v18, v18, 0x3a800000, v34
	v_rsq_f32_e32 v18, v18
	v_fmac_f32_e32 v81, v98, v98
	v_lshlrev_b32_e32 v100, 16, v16
	v_fmac_f32_e32 v81, v99, v99
	v_pk_mul_f32 v[36:37], v[36:37], v[18:19] op_sel_hi:[1,0]
	v_pk_mul_f32 v[60:61], v[84:85], v[18:19] op_sel_hi:[1,0]
	v_pk_mul_f32 v[38:39], v[38:39], v[18:19] op_sel_hi:[1,0]
	v_pk_mul_f32 v[62:63], v[86:87], v[18:19] op_sel_hi:[1,0]
	v_pk_mul_f32 v[40:41], v[40:41], v[18:19] op_sel_hi:[1,0]
	v_pk_mul_f32 v[84:85], v[88:89], v[18:19] op_sel_hi:[1,0]
	v_pk_mul_f32 v[42:43], v[42:43], v[18:19] op_sel:[1,0] op_sel_hi:[0,0]
	v_pk_mul_f32 v[86:87], v[90:91], v[18:19] op_sel_hi:[1,0]
	v_pk_mul_f32 v[60:61], v[12:13], v[60:61]
	v_pk_mul_f32 v[36:37], v[14:15], v[36:37]
	v_pk_mul_f32 v[62:63], v[8:9], v[62:63]
	v_pk_mul_f32 v[38:39], v[10:11], v[38:39]
	v_pk_mul_f32 v[84:85], v[4:5], v[84:85]
	v_pk_mul_f32 v[40:41], v[6:7], v[40:41]
	v_pk_mul_f32 v[86:87], v[0:1], v[86:87]
	v_pk_mul_f32 v[42:43], v[2:3], v[42:43]
	v_pk_fma_f32 v[46:47], v[46:47], v[36:37], v[66:67]
	v_pk_fma_f32 v[36:37], v[44:45], v[60:61], v[64:65]
	v_pk_fma_f32 v[44:45], v[54:55], v[38:39], v[78:79]
	v_pk_fma_f32 v[38:39], v[52:53], v[62:63], v[76:77]
	v_pk_fma_f32 v[50:51], v[50:51], v[40:41], v[74:75]
	v_pk_fma_f32 v[40:41], v[48:49], v[84:85], v[72:73]
	v_pk_fma_f32 v[48:49], v[58:59], v[42:43], v[70:71]
	v_pk_fma_f32 v[42:43], v[56:57], v[86:87], v[68:69]
	v_cvt_pk_bf16_f32 v36, v36, v37
	v_cvt_pk_bf16_f32 v37, v46, v47
	v_cvt_pk_bf16_f32 v38, v38, v39
	v_cvt_pk_bf16_f32 v39, v44, v45
	v_ashrrev_i32_e32 v18, 12, v80
	v_cvt_pk_bf16_f32 v40, v40, v41
	v_cvt_pk_bf16_f32 v41, v50, v51
	v_cvt_pk_bf16_f32 v42, v42, v43
	v_cvt_pk_bf16_f32 v43, v48, v49
	global_store_dwordx4 v[82:83], v[36:39], off
	global_store_dwordx4 v[82:83], v[40:43], off offset:16
	v_and_b32_e32 v101, 0xffff0000, v16
	v_mul_hi_i32_i24_e32 v37, 0x6000, v18
	v_mul_i32_i24_e32 v36, 0x6000, v18
	v_lshl_add_u64 v[36:37], s[66:67], 0, v[36:37]
	v_lshl_add_u64 v[48:49], v[36:37], 0, v[20:21]
	v_add_co_u32_e32 v50, vcc, s12, v48
	v_lshl_add_u64 v[68:69], v[48:49], 0, s[8:9]
	s_nop 0
	v_addc_co_u32_e32 v51, vcc, 0, v49, vcc
	v_cmp_eq_u32_e32 vcc, v160, v18
	s_cbranch_vccz .Lp6_reload
	v_mov_b64_e32 v[36:37], v[128:129]
	v_mov_b64_e32 v[38:39], v[130:131]
	v_mov_b64_e32 v[40:41], v[132:133]
	v_mov_b64_e32 v[42:43], v[134:135]
	v_mov_b64_e32 v[44:45], v[136:137]
	v_mov_b64_e32 v[46:47], v[138:139]
	v_mov_b64_e32 v[48:49], v[140:141]
	v_mov_b64_e32 v[50:51], v[142:143]
	v_mov_b64_e32 v[52:53], v[144:145]
	v_mov_b64_e32 v[54:55], v[146:147]
	v_mov_b64_e32 v[56:57], v[148:149]
	v_mov_b64_e32 v[58:59], v[150:151]
	v_mov_b64_e32 v[60:61], v[152:153]
	v_mov_b64_e32 v[62:63], v[154:155]
	v_mov_b64_e32 v[64:65], v[156:157]
	v_mov_b64_e32 v[66:67], v[158:159]
	s_branch .Lp6_join
.Lp6_reload:
	global_load_dwordx4 v[36:39], v[50:51], off
	global_load_dwordx4 v[40:43], v[68:69], off offset:32
	global_load_dwordx4 v[44:47], v[68:69], off offset:16
	v_add_co_u32_e32 v72, vcc, s13, v48
	v_lshl_add_u64 v[70:71], v[48:49], 0, s[10:11]
	s_nop 0
	v_addc_co_u32_e32 v73, vcc, 0, v49, vcc
	global_load_dwordx4 v[48:51], v[72:73], off
	global_load_dwordx4 v[52:55], v[68:69], off offset:48
	global_load_dwordx4 v[56:59], v[70:71], off offset:16
	global_load_dwordx4 v[60:63], v[70:71], off offset:48
	global_load_dwordx4 v[64:67], v[70:71], off offset:32
	s_waitcnt vmcnt(0)
.Lp6_join:
	v_fmac_f32_e32 v81, v100, v100
	v_lshlrev_b32_e32 v16, 16, v17
	v_fmac_f32_e32 v81, v101, v101
	v_and_b32_e32 v17, 0xffff0000, v17
	v_fmac_f32_e32 v81, v16, v16
	v_fmac_f32_e32 v81, v17, v17
	v_fmac_f32_e32 v81, v102, v102
	v_and_b32_e32 v18, 0xffff0000, v19
	v_lshlrev_b32_e32 v19, 16, v19
	v_fmac_f32_e32 v81, v103, v103
	v_pk_mul_f32 v[68:69], v[18:19], v[18:19]
	v_pk_add_f32 v[36:37], v[36:37], 1.0 op_sel_hi:[1,0]
	v_add_f32_e32 v69, v69, v81
	v_add_f32_e32 v68, v68, v69
	ds_bpermute_b32 v69, v28, v68
	v_pk_add_f32 v[44:45], v[44:45], 1.0 op_sel_hi:[1,0]
	v_pk_add_f32 v[42:43], v[42:43], 1.0 op_sel_hi:[1,0]
	v_pk_add_f32 v[40:41], v[40:41], 1.0 op_sel_hi:[1,0]
	s_waitcnt lgkmcnt(0)
	v_add_f32_e32 v68, v68, v69
	ds_bpermute_b32 v69, v29, v68
	s_waitcnt lgkmcnt(0)
	v_add_f32_e32 v68, v68, v69
	ds_bpermute_b32 v69, v30, v68
	s_waitcnt lgkmcnt(0)
	v_add_f32_e32 v68, v68, v69
	ds_bpermute_b32 v69, v31, v68
	s_waitcnt lgkmcnt(0)
	v_add_f32_e32 v68, v68, v69
	ds_bpermute_b32 v69, v32, v68
	s_waitcnt lgkmcnt(0)
	v_add_f32_e32 v68, v68, v69
	ds_bpermute_b32 v69, v33, v68
	s_waitcnt lgkmcnt(0)
	v_add_f32_e32 v68, v68, v69
	v_fmamk_f32 v68, v68, 0x3a800000, v34
	v_rsq_f32_e32 v68, v68
	s_nop 0
	v_pk_mul_f32 v[70:71], v[94:95], v[68:69] op_sel_hi:[1,0]
	v_pk_mul_f32 v[72:73], v[92:93], v[68:69] op_sel_hi:[1,0]
	v_pk_mul_f32 v[74:75], v[98:99], v[68:69] op_sel_hi:[1,0]
	v_pk_mul_f32 v[76:77], v[96:97], v[68:69] op_sel_hi:[1,0]
	v_pk_mul_f32 v[78:79], v[100:101], v[68:69] op_sel_hi:[1,0]
	v_pk_mul_f32 v[80:81], v[18:19], v[68:69] op_sel:[1,0] op_sel_hi:[0,0]
	v_pk_mul_f32 v[18:19], v[102:103], v[68:69] op_sel_hi:[1,0]
	v_pk_mul_f32 v[16:17], v[16:17], v[68:69] op_sel_hi:[1,0]
	v_pk_mul_f32 v[68:69], v[12:13], v[72:73]
	v_pk_mul_f32 v[70:71], v[14:15], v[70:71]
	v_pk_mul_f32 v[72:73], v[8:9], v[76:77]
	v_pk_mul_f32 v[74:75], v[10:11], v[74:75]
	v_pk_mul_f32 v[76:77], v[4:5], v[78:79]
	v_pk_mul_f32 v[78:79], v[0:1], v[18:19]
	v_pk_add_f32 v[18:19], v[38:39], 1.0 op_sel_hi:[1,0]
	v_pk_add_f32 v[38:39], v[46:47], 1.0 op_sel_hi:[1,0]
	v_pk_mul_f32 v[16:17], v[6:7], v[16:17]
	v_pk_fma_f32 v[18:19], v[18:19], v[70:71], v[50:51]
	v_pk_fma_f32 v[36:37], v[36:37], v[68:69], v[48:49]
	v_pk_fma_f32 v[38:39], v[38:39], v[74:75], v[58:59]
	v_pk_fma_f32 v[44:45], v[44:45], v[72:73], v[56:57]
	v_pk_fma_f32 v[42:43], v[42:43], v[16:17], v[66:67]
	v_pk_fma_f32 v[40:41], v[40:41], v[76:77], v[64:65]
	v_cvt_pk_bf16_f32 v16, v36, v37
	v_cvt_pk_bf16_f32 v17, v18, v19
	v_cvt_pk_bf16_f32 v18, v44, v45
	v_cvt_pk_bf16_f32 v19, v38, v39
	v_cvt_pk_bf16_f32 v36, v40, v41
	v_cvt_pk_bf16_f32 v37, v42, v43
	v_pk_mul_f32 v[38:39], v[2:3], v[80:81]
	v_pk_add_f32 v[40:41], v[54:55], 1.0 op_sel_hi:[1,0]
	v_pk_add_f32 v[42:43], v[52:53], 1.0 op_sel_hi:[1,0]
	global_store_dwordx4 v[26:27], v[16:19], off
	v_pk_fma_f32 v[40:41], v[40:41], v[38:39], v[62:63]
	v_pk_fma_f32 v[38:39], v[42:43], v[78:79], v[60:61]
	v_add_u32_e32 v16, s3, v35
	v_cmp_lt_i32_e32 vcc, s14, v16
	v_cvt_pk_bf16_f32 v38, v38, v39
	v_cvt_pk_bf16_f32 v39, v40, v41
	s_or_b64 s[6:7], vcc, s[6:7]
	global_store_dwordx4 v[26:27], v[36:39], off offset:16
	s_andn2_b64 exec, exec, s[6:7]
	s_cbranch_execnz .LBB0_617

; #define PG8_STAGE(bufoff, gbase, voff) do { _Pragma("unroll") for (int _i = 0; _i < 2; ++_i) \
;         __builtin_amdgcn_global_load_lds((const unsigned*)((const char*)(gbase) + (voff)[_i]), (LAS unsigned*)(lds + (bufoff) + ldsw + _i * 8192), 16, 0, 0); } while (0)
; #define PG8_LDA(dst, b, h) do { _Pragma("unroll") for (int m = 0; m < 4; ++m) _Pragma("unroll") for (int k = 0; k < 2; ++k) dst[m][k] = *(const LAS bf16x8*)(lds + PG8_SA(b, h) + aoff + m * 2048 + k * 1024); } while (0)
; #define PG8_LDB(dst, b, h) do { _Pragma("unroll") for (int n = 0; n < 2; ++n) _Pragma("unroll") for (int k = 0; k < 2; ++k) dst[n][k] = *(const LAS bf16x8*)(lds + PG8_SB(b, h) + boff + n * 2048 + k * 1024); } while (0)
; #define PG8_MMA(ai, bj, At, Bt) do { __builtin_amdgcn_s_setprio(1); _Pragma("unroll") for (int m = 0; m < 4; ++m) _Pragma("unroll") for (int n = 0; n < 2; ++n) _Pragma("unroll") for (int k = 0; k < 2; ++k) \
;         acc[ai][bj][m][n] = __builtin_amdgcn_mfma_f32_16x16x32_bf16(Bt[n][k], At[m][k], acc[ai][bj][m][n], 0, 0, 0); __builtin_amdgcn_s_setprio(0); } while (0)
; #define PG8_WAIT_V(n) asm volatile("s_waitcnt vmcnt(" #n ")" ::: "memory")
; #define PG8_WAIT_L(n) asm volatile("s_waitcnt lgkmcnt(" #n ")" ::: "memory")
; #define PG8_BAR __builtin_amdgcn_s_barrier()
; template <class Epi, class Sched, bool ALIGN_EPI, bool SP2>
; __device__ __forceinline__ void gemm_phase(LAS unsigned char* lds, const Gemm g, const Sched& S, const Epi& E) {
;     ...
;         for (int t = 0; t < nt; t += 2) {
;             const bool last = (t == nt - 2);
;             const char* a1 = cA + (size_t)(t + 1) * kstep;
;             const char* a2 = last ? nA : cA + (size_t)(t + 2) * kstep; const char* b2 = last ? nB : cB + (size_t)(t + 2) * kstep;
;             const char* a3 = a2 + kstep; const char* b3 = b2 + kstep;
;             if constexpr (SP2) {
;             PG8_LDB(B0, 0, 0); PG8_LDB(B1, 0, 1); PG8_SCHED; PG8_LDA(At, 0, 0); PG8_STAGE(PG8_SA(1, 1), a1 + hstep, voffA);
;             PG8_WAIT_V(8); PG8_WAIT_L(0); PG8_BAR; PG8_MMA(0, 0, At, B0); PG8_MMA(0, 1, At, B1); PG8_BAR; PG8_SCHED;
;             PG8_LDA(At, 0, 1); PG8_STAGE(PG8_SB(0, 0), b2, voffB); PG8_STAGE(PG8_SB(0, 1), b2 + hstep, voffB); PG8_STAGE(PG8_SA(0, 0), a2, voffA);
;             PG8_WAIT_V(8); PG8_WAIT_L(0); PG8_BAR; PG8_MMA(1, 0, At, B0); PG8_MMA(1, 1, At, B1); PG8_BAR; PG8_SCHED;
.LBB0_683:
	s_add_i32 m0, s23, 0xc000
	s_nop 0
	global_load_lds_dwordx4 v136, s[24:25]
	s_add_i32 m0, s23, 0xe000
	s_nop 0
	global_load_lds_dwordx4 v138, s[24:25]
	ds_read_b128 v[150:153], v147
	ds_read_b128 v[154:157], v147 offset:1024
	ds_read_b128 v[158:161], v147 offset:2048
	ds_read_b128 v[162:165], v147 offset:3072
	ds_read_b128 v[166:169], v148
	ds_read_b128 v[170:173], v148 offset:1024
	ds_read_b128 v[176:179], v148 offset:2048
	ds_read_b128 v[180:183], v148 offset:3072
	ds_read_b128 v[184:187], v149
	ds_read_b128 v[188:191], v149 offset:1024
	ds_read_b128 v[192:195], v149 offset:2048
	ds_read_b128 v[196:199], v149 offset:3072
	ds_read_b128 v[200:203], v149 offset:4096
	ds_read_b128 v[204:207], v149 offset:5120
	ds_read_b128 v[208:211], v149 offset:6144
	ds_read_b128 v[212:215], v149 offset:7168
	s_add_u32 s26, s24, 0xfffc0080
	s_addc_u32 s27, s25, -1
	s_cmp_eq_u32 s52, 12
	s_cselect_b32 s29, s15, s27
	s_cselect_b32 s28, s48, s26
	s_cselect_b32 s27, s17, s51
	s_cselect_b32 s26, s49, s50
	s_waitcnt vmcnt(8)
	s_waitcnt lgkmcnt(0)
	s_barrier
	s_setprio 1
	s_waitcnt lgkmcnt(0)
	v_mfma_f32_16x16x32_bf16 v[124:127], v[150:153], v[184:187], v[124:127]
	v_mfma_f32_16x16x32_bf16 v[120:123], v[158:161], v[184:187], v[120:123]
	v_mfma_f32_16x16x32_bf16 v[108:111], v[150:153], v[192:195], v[108:111]
	v_mfma_f32_16x16x32_bf16 v[104:107], v[158:161], v[192:195], v[104:107]
	v_mfma_f32_16x16x32_bf16 v[92:95], v[150:153], v[200:203], v[92:95]
	v_mfma_f32_16x16x32_bf16 v[88:91], v[158:161], v[200:203], v[88:91]
	v_mfma_f32_16x16x32_bf16 v[76:79], v[150:153], v[208:211], v[76:79]
	v_mfma_f32_16x16x32_bf16 v[72:75], v[158:161], v[208:211], v[72:75]
	v_mfma_f32_16x16x32_bf16 v[124:127], v[154:157], v[188:191], v[124:127]
	v_mfma_f32_16x16x32_bf16 v[120:123], v[162:165], v[188:191], v[120:123]
	v_mfma_f32_16x16x32_bf16 v[108:111], v[154:157], v[196:199], v[108:111]
	v_mfma_f32_16x16x32_bf16 v[104:107], v[162:165], v[196:199], v[104:107]
	v_mfma_f32_16x16x32_bf16 v[92:95], v[154:157], v[204:207], v[92:95]
	v_mfma_f32_16x16x32_bf16 v[88:91], v[162:165], v[204:207], v[88:91]
	v_mfma_f32_16x16x32_bf16 v[76:79], v[154:157], v[212:215], v[76:79]
	v_mfma_f32_16x16x32_bf16 v[72:75], v[162:165], v[212:215], v[72:75]
	s_setprio 0
	s_setprio 1
	v_mfma_f32_16x16x32_bf16 v[116:119], v[166:169], v[184:187], v[116:119]
	v_mfma_f32_16x16x32_bf16 v[112:115], v[176:179], v[184:187], v[112:115]
	v_mfma_f32_16x16x32_bf16 v[100:103], v[166:169], v[192:195], v[100:103]
	v_mfma_f32_16x16x32_bf16 v[96:99], v[176:179], v[192:195], v[96:99]
	v_mfma_f32_16x16x32_bf16 v[84:87], v[166:169], v[200:203], v[84:87]
	v_mfma_f32_16x16x32_bf16 v[80:83], v[176:179], v[200:203], v[80:83]
	v_mfma_f32_16x16x32_bf16 v[68:71], v[166:169], v[208:211], v[68:71]
	v_mfma_f32_16x16x32_bf16 v[64:67], v[176:179], v[208:211], v[64:67]
	v_mfma_f32_16x16x32_bf16 v[116:119], v[170:173], v[188:191], v[116:119]
	v_mfma_f32_16x16x32_bf16 v[112:115], v[180:183], v[188:191], v[112:115]
	v_mfma_f32_16x16x32_bf16 v[100:103], v[170:173], v[196:199], v[100:103]
	v_mfma_f32_16x16x32_bf16 v[96:99], v[180:183], v[196:199], v[96:99]
	v_mfma_f32_16x16x32_bf16 v[84:87], v[170:173], v[204:207], v[84:87]
	v_mfma_f32_16x16x32_bf16 v[80:83], v[180:183], v[204:207], v[80:83]
	v_mfma_f32_16x16x32_bf16 v[68:71], v[170:173], v[212:215], v[68:71]
	v_mfma_f32_16x16x32_bf16 v[64:67], v[180:183], v[212:215], v[64:67]
	s_setprio 0
	s_barrier
	s_add_i32 s53, s44, s30
	s_mov_b32 m0, s53
	s_nop 0
	global_load_lds_dwordx4 v132, s[26:27]
	s_add_i32 m0, s53, 0x2000
	s_add_u32 s54, s26, 0x40000
	s_addc_u32 s55, s27, 0
	s_add_i32 s53, s45, s30
	global_load_lds_dwordx4 v128, s[26:27]
	s_mov_b32 m0, s53
	s_nop 0
	global_load_lds_dwordx4 v132, s[54:55]
	s_add_i32 m0, s53, 0x2000
	s_nop 0
	global_load_lds_dwordx4 v128, s[54:55]
	s_mov_b32 m0, s23
	s_nop 0
	global_load_lds_dwordx4 v134, s[28:29]
	s_mov_b32 m0, s34
	s_nop 0
	global_load_lds_dwordx4 v130, s[28:29]
	ds_read_b128 v[184:187], v149 offset:16384
	ds_read_b128 v[188:191], v149 offset:17408
	ds_read_b128 v[192:195], v149 offset:18432
	ds_read_b128 v[196:199], v149 offset:19456
	ds_read_b128 v[200:203], v149 offset:20480
	ds_read_b128 v[204:207], v149 offset:21504
	ds_read_b128 v[208:211], v149 offset:22528
	ds_read_b128 v[212:215], v149 offset:23552
	s_waitcnt vmcnt(8)
	s_waitcnt lgkmcnt(0)
	s_barrier
	s_setprio 1
	s_waitcnt lgkmcnt(0)
	v_mfma_f32_16x16x32_bf16 v[60:63], v[150:153], v[184:187], v[60:63]
	v_mfma_f32_16x16x32_bf16 v[56:59], v[158:161], v[184:187], v[56:59]
	v_mfma_f32_16x16x32_bf16 v[44:47], v[150:153], v[192:195], v[44:47]
	v_mfma_f32_16x16x32_bf16 v[40:43], v[158:161], v[192:195], v[40:43]
	v_mfma_f32_16x16x32_bf16 v[28:31], v[150:153], v[200:203], v[28:31]
	v_mfma_f32_16x16x32_bf16 v[24:27], v[158:161], v[200:203], v[24:27]
	v_mfma_f32_16x16x32_bf16 v[12:15], v[150:153], v[208:211], v[12:15]
	v_mfma_f32_16x16x32_bf16 v[8:11], v[158:161], v[208:211], v[8:11]
	v_mfma_f32_16x16x32_bf16 v[60:63], v[154:157], v[188:191], v[60:63]
	v_mfma_f32_16x16x32_bf16 v[56:59], v[162:165], v[188:191], v[56:59]
	v_mfma_f32_16x16x32_bf16 v[44:47], v[154:157], v[196:199], v[44:47]
	v_mfma_f32_16x16x32_bf16 v[40:43], v[162:165], v[196:199], v[40:43]
	v_mfma_f32_16x16x32_bf16 v[28:31], v[154:157], v[204:207], v[28:31]
	v_mfma_f32_16x16x32_bf16 v[24:27], v[162:165], v[204:207], v[24:27]
	v_mfma_f32_16x16x32_bf16 v[12:15], v[154:157], v[212:215], v[12:15]
	v_mfma_f32_16x16x32_bf16 v[8:11], v[162:165], v[212:215], v[8:11]
	s_setprio 0
	s_setprio 1
	v_mfma_f32_16x16x32_bf16 v[52:55], v[166:169], v[184:187], v[52:55]
	v_mfma_f32_16x16x32_bf16 v[48:51], v[176:179], v[184:187], v[48:51]
	v_mfma_f32_16x16x32_bf16 v[36:39], v[166:169], v[192:195], v[36:39]
	v_mfma_f32_16x16x32_bf16 v[32:35], v[176:179], v[192:195], v[32:35]
	v_mfma_f32_16x16x32_bf16 v[20:23], v[166:169], v[200:203], v[20:23]
	v_mfma_f32_16x16x32_bf16 v[16:19], v[176:179], v[200:203], v[16:19]
	v_mfma_f32_16x16x32_bf16 v[4:7], v[166:169], v[208:211], v[4:7]
	v_mfma_f32_16x16x32_bf16 v[0:3], v[176:179], v[208:211], v[0:3]
	v_mfma_f32_16x16x32_bf16 v[52:55], v[170:173], v[188:191], v[52:55]
	v_mfma_f32_16x16x32_bf16 v[48:51], v[180:183], v[188:191], v[48:51]
	v_mfma_f32_16x16x32_bf16 v[36:39], v[170:173], v[196:199], v[36:39]
	v_mfma_f32_16x16x32_bf16 v[32:35], v[180:183], v[196:199], v[32:35]
	v_mfma_f32_16x16x32_bf16 v[20:23], v[170:173], v[204:207], v[20:23]
	v_mfma_f32_16x16x32_bf16 v[16:19], v[180:183], v[204:207], v[16:19]
	v_mfma_f32_16x16x32_bf16 v[4:7], v[170:173], v[212:215], v[4:7]
	v_mfma_f32_16x16x32_bf16 v[0:3], v[180:183], v[212:215], v[0:3]
	s_setprio 0
	s_barrier
; #define PG8_STAGE(bufoff, gbase, voff) do { _Pragma("unroll") for (int _i = 0; _i < 2; ++_i) \
;         __builtin_amdgcn_global_load_lds((const unsigned*)((const char*)(gbase) + (voff)[_i]), (LAS unsigned*)(lds + (bufoff) + ldsw + _i * 8192), 16, 0, 0); } while (0)
; #define PG8_LDA(dst, b, h) do { _Pragma("unroll") for (int m = 0; m < 4; ++m) _Pragma("unroll") for (int k = 0; k < 2; ++k) dst[m][k] = *(const LAS bf16x8*)(lds + PG8_SA(b, h) + aoff + m * 2048 + k * 1024); } while (0)
; #define PG8_LDB(dst, b, h) do { _Pragma("unroll") for (int n = 0; n < 2; ++n) _Pragma("unroll") for (int k = 0; k < 2; ++k) dst[n][k] = *(const LAS bf16x8*)(lds + PG8_SB(b, h) + boff + n * 2048 + k * 1024); } while (0)
; #define PG8_MMA(ai, bj, At, Bt) do { __builtin_amdgcn_s_setprio(1); _Pragma("unroll") for (int m = 0; m < 4; ++m) _Pragma("unroll") for (int n = 0; n < 2; ++n) _Pragma("unroll") for (int k = 0; k < 2; ++k) \
;         acc[ai][bj][m][n] = __builtin_amdgcn_mfma_f32_16x16x32_bf16(Bt[n][k], At[m][k], acc[ai][bj][m][n], 0, 0, 0); __builtin_amdgcn_s_setprio(0); } while (0)
; #define PG8_WAIT_V(n) asm volatile("s_waitcnt vmcnt(" #n ")" ::: "memory")
; #define PG8_WAIT_L(n) asm volatile("s_waitcnt lgkmcnt(" #n ")" ::: "memory")
; #define PG8_BAR __builtin_amdgcn_s_barrier()
; #define PG8_SCHED __builtin_amdgcn_sched_barrier(0)
; template <class Epi, class Sched, bool ALIGN_EPI, bool SP2>
; __device__ __forceinline__ void gemm_phase(LAS unsigned char* lds, const Gemm g, const Sched& S, const Epi& E) {
;     ...
;             PG8_LDB(B0, 1, 0); PG8_LDB(B1, 1, 1); PG8_SCHED; PG8_LDA(At, 1, 0); PG8_STAGE(PG8_SA(0, 1), a2 + hstep, voffA);
;             PG8_WAIT_V(8); PG8_WAIT_L(0); PG8_BAR; PG8_MMA(0, 0, At, B0); PG8_MMA(0, 1, At, B1); PG8_BAR; PG8_SCHED;
;             PG8_LDA(At, 1, 1); PG8_STAGE(PG8_SB(1, 0), b3, voffB); PG8_STAGE(PG8_SB(1, 1), b3 + hstep, voffB); PG8_STAGE(PG8_SA(1, 0), a3, voffA);
;             PG8_WAIT_V(8); PG8_WAIT_L(0); PG8_BAR; PG8_MMA(1, 0, At, B0); PG8_MMA(1, 1, At, B1); PG8_BAR; PG8_SCHED;
;     ...
;         }
;         if constexpr (ALIGN_EPI) { if (wr == 0) PG8_BAR; }
	s_add_i32 s53, 0, 0x18000
	s_add_i32 s54, 0, 0x1c000
	v_add_u32_e32 v162, s53, v145
	v_add_u32_e32 v174, s54, v145
	s_add_u32 s28, s28, 0x40000
	s_addc_u32 s29, s29, 0
	s_mov_b32 m0, s35
	s_nop 0
	global_load_lds_dwordx4 v134, s[28:29]
	s_mov_b32 m0, s36
	s_nop 0
	global_load_lds_dwordx4 v130, s[28:29]
	ds_read_b128 v[150:153], v162
	ds_read_b128 v[154:157], v162 offset:1024
	ds_read_b128 v[158:161], v162 offset:2048
	ds_read_b128 v[162:165], v162 offset:3072
	ds_read_b128 v[166:169], v174
	ds_read_b128 v[170:173], v174 offset:1024
	ds_read_b128 v[176:179], v174 offset:2048
	ds_read_b128 v[180:183], v174 offset:3072
	ds_read_b128 v[184:187], v149 offset:32768
	ds_read_b128 v[188:191], v149 offset:33792
	ds_read_b128 v[192:195], v149 offset:34816
	ds_read_b128 v[196:199], v149 offset:35840
	ds_read_b128 v[200:203], v149 offset:36864
	ds_read_b128 v[204:207], v149 offset:37888
	ds_read_b128 v[208:211], v149 offset:38912
	ds_read_b128 v[212:215], v149 offset:39936
	s_waitcnt vmcnt(8)
	s_waitcnt lgkmcnt(0)
	s_barrier
	s_setprio 1
	s_waitcnt lgkmcnt(0)
	v_mfma_f32_16x16x32_bf16 v[124:127], v[150:153], v[184:187], v[124:127]
	v_mfma_f32_16x16x32_bf16 v[120:123], v[158:161], v[184:187], v[120:123]
	v_mfma_f32_16x16x32_bf16 v[108:111], v[150:153], v[192:195], v[108:111]
	v_mfma_f32_16x16x32_bf16 v[104:107], v[158:161], v[192:195], v[104:107]
	v_mfma_f32_16x16x32_bf16 v[92:95], v[150:153], v[200:203], v[92:95]
	v_mfma_f32_16x16x32_bf16 v[88:91], v[158:161], v[200:203], v[88:91]
	v_mfma_f32_16x16x32_bf16 v[76:79], v[150:153], v[208:211], v[76:79]
	v_mfma_f32_16x16x32_bf16 v[72:75], v[158:161], v[208:211], v[72:75]
	v_mfma_f32_16x16x32_bf16 v[124:127], v[154:157], v[188:191], v[124:127]
	v_mfma_f32_16x16x32_bf16 v[120:123], v[162:165], v[188:191], v[120:123]
	v_mfma_f32_16x16x32_bf16 v[108:111], v[154:157], v[196:199], v[108:111]
	v_mfma_f32_16x16x32_bf16 v[104:107], v[162:165], v[196:199], v[104:107]
	v_mfma_f32_16x16x32_bf16 v[92:95], v[154:157], v[204:207], v[92:95]
	v_mfma_f32_16x16x32_bf16 v[88:91], v[162:165], v[204:207], v[88:91]
	v_mfma_f32_16x16x32_bf16 v[76:79], v[154:157], v[212:215], v[76:79]
	v_mfma_f32_16x16x32_bf16 v[72:75], v[162:165], v[212:215], v[72:75]
	s_setprio 0
	s_setprio 1
	v_mfma_f32_16x16x32_bf16 v[116:119], v[166:169], v[184:187], v[116:119]
	v_mfma_f32_16x16x32_bf16 v[112:115], v[176:179], v[184:187], v[112:115]
	v_mfma_f32_16x16x32_bf16 v[100:103], v[166:169], v[192:195], v[100:103]
	v_mfma_f32_16x16x32_bf16 v[96:99], v[176:179], v[192:195], v[96:99]
	v_mfma_f32_16x16x32_bf16 v[84:87], v[166:169], v[200:203], v[84:87]
	v_mfma_f32_16x16x32_bf16 v[80:83], v[176:179], v[200:203], v[80:83]
	v_mfma_f32_16x16x32_bf16 v[68:71], v[166:169], v[208:211], v[68:71]
	v_mfma_f32_16x16x32_bf16 v[64:67], v[176:179], v[208:211], v[64:67]
	v_mfma_f32_16x16x32_bf16 v[116:119], v[170:173], v[188:191], v[116:119]
	v_mfma_f32_16x16x32_bf16 v[112:115], v[180:183], v[188:191], v[112:115]
	v_mfma_f32_16x16x32_bf16 v[100:103], v[170:173], v[196:199], v[100:103]
	v_mfma_f32_16x16x32_bf16 v[96:99], v[180:183], v[196:199], v[96:99]
	v_mfma_f32_16x16x32_bf16 v[84:87], v[170:173], v[204:207], v[84:87]
	v_mfma_f32_16x16x32_bf16 v[80:83], v[180:183], v[204:207], v[80:83]
	v_mfma_f32_16x16x32_bf16 v[68:71], v[170:173], v[212:215], v[68:71]
	v_mfma_f32_16x16x32_bf16 v[64:67], v[180:183], v[212:215], v[64:67]
	s_setprio 0
	s_barrier
	s_add_u32 s100, s28, 0xfffc0080
	s_addc_u32 s101, s29, -1
	s_add_u32 s98, s26, 0x80
	s_addc_u32 s99, s27, 0
	s_add_i32 s28, s53, s30
	s_mov_b32 m0, s28
	s_nop 0
	global_load_lds_dwordx4 v132, s[98:99]
	s_add_i32 m0, s28, 0x2000
	s_add_u32 s26, s26, 0x40080
	s_addc_u32 s27, s27, 0
	s_add_i32 s28, s54, s30
	global_load_lds_dwordx4 v128, s[98:99]
	s_mov_b32 m0, s28
	s_nop 0
	global_load_lds_dwordx4 v132, s[26:27]
	s_add_i32 m0, s28, 0x2000
	s_nop 0
	global_load_lds_dwordx4 v128, s[26:27]
	s_mov_b32 m0, s38
	s_nop 0
	global_load_lds_dwordx4 v134, s[100:101]
	s_mov_b32 m0, s39
	s_nop 0
	global_load_lds_dwordx4 v130, s[100:101]
	ds_read_b128 v[184:187], v149 offset:49152
	ds_read_b128 v[188:191], v149 offset:50176
	ds_read_b128 v[192:195], v149 offset:51200
	ds_read_b128 v[196:199], v149 offset:52224
	ds_read_b128 v[200:203], v149 offset:53248
	ds_read_b128 v[204:207], v149 offset:54272
	ds_read_b128 v[208:211], v149 offset:55296
	ds_read_b128 v[212:215], v149 offset:56320
	s_waitcnt vmcnt(8)
	s_waitcnt lgkmcnt(0)
	s_barrier
	s_setprio 1
	s_waitcnt lgkmcnt(0)
	v_mfma_f32_16x16x32_bf16 v[60:63], v[150:153], v[184:187], v[60:63]
	v_mfma_f32_16x16x32_bf16 v[56:59], v[158:161], v[184:187], v[56:59]
	v_mfma_f32_16x16x32_bf16 v[44:47], v[150:153], v[192:195], v[44:47]
	v_mfma_f32_16x16x32_bf16 v[40:43], v[158:161], v[192:195], v[40:43]
	v_mfma_f32_16x16x32_bf16 v[28:31], v[150:153], v[200:203], v[28:31]
	v_mfma_f32_16x16x32_bf16 v[24:27], v[158:161], v[200:203], v[24:27]
	v_mfma_f32_16x16x32_bf16 v[12:15], v[150:153], v[208:211], v[12:15]
	v_mfma_f32_16x16x32_bf16 v[8:11], v[158:161], v[208:211], v[8:11]
	v_mfma_f32_16x16x32_bf16 v[60:63], v[154:157], v[188:191], v[60:63]
	v_mfma_f32_16x16x32_bf16 v[56:59], v[162:165], v[188:191], v[56:59]
	v_mfma_f32_16x16x32_bf16 v[44:47], v[154:157], v[196:199], v[44:47]
	v_mfma_f32_16x16x32_bf16 v[40:43], v[162:165], v[196:199], v[40:43]
	v_mfma_f32_16x16x32_bf16 v[28:31], v[154:157], v[204:207], v[28:31]
	v_mfma_f32_16x16x32_bf16 v[24:27], v[162:165], v[204:207], v[24:27]
	v_mfma_f32_16x16x32_bf16 v[12:15], v[154:157], v[212:215], v[12:15]
	v_mfma_f32_16x16x32_bf16 v[8:11], v[162:165], v[212:215], v[8:11]
	s_setprio 0
	s_setprio 1
	v_mfma_f32_16x16x32_bf16 v[52:55], v[166:169], v[184:187], v[52:55]
	v_mfma_f32_16x16x32_bf16 v[48:51], v[176:179], v[184:187], v[48:51]
	v_mfma_f32_16x16x32_bf16 v[36:39], v[166:169], v[192:195], v[36:39]
	v_mfma_f32_16x16x32_bf16 v[32:35], v[176:179], v[192:195], v[32:35]
	v_mfma_f32_16x16x32_bf16 v[20:23], v[166:169], v[200:203], v[20:23]
	v_mfma_f32_16x16x32_bf16 v[16:19], v[176:179], v[200:203], v[16:19]
	v_mfma_f32_16x16x32_bf16 v[4:7], v[166:169], v[208:211], v[4:7]
	v_mfma_f32_16x16x32_bf16 v[0:3], v[176:179], v[208:211], v[0:3]
	v_mfma_f32_16x16x32_bf16 v[52:55], v[170:173], v[188:191], v[52:55]
	v_mfma_f32_16x16x32_bf16 v[48:51], v[180:183], v[188:191], v[48:51]
	v_mfma_f32_16x16x32_bf16 v[36:39], v[170:173], v[196:199], v[36:39]
	v_mfma_f32_16x16x32_bf16 v[32:35], v[180:183], v[196:199], v[32:35]
	v_mfma_f32_16x16x32_bf16 v[20:23], v[170:173], v[204:207], v[20:23]
	v_mfma_f32_16x16x32_bf16 v[16:19], v[180:183], v[204:207], v[16:19]
	v_mfma_f32_16x16x32_bf16 v[4:7], v[170:173], v[212:215], v[4:7]
	v_mfma_f32_16x16x32_bf16 v[0:3], v[180:183], v[212:215], v[0:3]
	s_setprio 0
	s_barrier
	s_add_i32 s52, s52, 2
	s_add_u32 s24, s24, 0x100
	s_addc_u32 s25, s25, 0
	s_add_u32 s50, s50, 0x100
	s_addc_u32 s51, s51, 0
	s_cmp_gt_u32 s52, 13
	s_cbranch_scc0 .LBB0_683
	s_and_b64 vcc, exec, s[12:13]
	s_cbranch_vccz .LBB0_686
	s_barrier

; #define PG8_STAGE(bufoff, gbase, voff) do { _Pragma("unroll") for (int _i = 0; _i < 2; ++_i) \
;         __builtin_amdgcn_global_load_lds((const unsigned*)((const char*)(gbase) + (voff)[_i]), (LAS unsigned*)(lds + (bufoff) + ldsw + _i * 8192), 16, 0, 0); } while (0)
; #define PG8_LDA(dst, b, h) do { _Pragma("unroll") for (int m = 0; m < 4; ++m) _Pragma("unroll") for (int k = 0; k < 2; ++k) dst[m][k] = *(const LAS bf16x8*)(lds + PG8_SA(b, h) + aoff + m * 2048 + k * 1024); } while (0)
; #define PG8_LDB(dst, b, h) do { _Pragma("unroll") for (int n = 0; n < 2; ++n) _Pragma("unroll") for (int k = 0; k < 2; ++k) dst[n][k] = *(const LAS bf16x8*)(lds + PG8_SB(b, h) + boff + n * 2048 + k * 1024); } while (0)
; #define PG8_MMA(ai, bj, At, Bt) do { __builtin_amdgcn_s_setprio(1); _Pragma("unroll") for (int m = 0; m < 4; ++m) _Pragma("unroll") for (int n = 0; n < 2; ++n) _Pragma("unroll") for (int k = 0; k < 2; ++k) \
;         acc[ai][bj][m][n] = __builtin_amdgcn_mfma_f32_16x16x32_bf16(Bt[n][k], At[m][k], acc[ai][bj][m][n], 0, 0, 0); __builtin_amdgcn_s_setprio(0); } while (0)
; #define PG8_WAIT_V(n) asm volatile("s_waitcnt vmcnt(" #n ")" ::: "memory")
; #define PG8_WAIT_L(n) asm volatile("s_waitcnt lgkmcnt(" #n ")" ::: "memory")
; #define PG8_BAR __builtin_amdgcn_s_barrier()
; template <class Epi, class Sched, bool ALIGN_EPI, bool SP2>
; __device__ __forceinline__ void gemm_phase(LAS unsigned char* lds, const Gemm g, const Sched& S, const Epi& E) {
;     ...
;         for (int t = 0; t < nt; t += 2) {
;             const bool last = (t == nt - 2);
;             const char* a1 = cA + (size_t)(t + 1) * kstep;
;             const char* a2 = last ? nA : cA + (size_t)(t + 2) * kstep; const char* b2 = last ? nB : cB + (size_t)(t + 2) * kstep;
;             const char* a3 = a2 + kstep; const char* b3 = b2 + kstep;
;             if constexpr (SP2) {
;             PG8_LDB(B0, 0, 0); PG8_LDB(B1, 0, 1); PG8_SCHED; PG8_LDA(At, 0, 0); PG8_STAGE(PG8_SA(1, 1), a1 + hstep, voffA);
;             PG8_WAIT_V(8); PG8_WAIT_L(0); PG8_BAR; PG8_MMA(0, 0, At, B0); PG8_MMA(0, 1, At, B1); PG8_BAR; PG8_SCHED;
;             PG8_LDA(At, 0, 1); PG8_STAGE(PG8_SB(0, 0), b2, voffB); PG8_STAGE(PG8_SB(0, 1), b2 + hstep, voffB); PG8_STAGE(PG8_SA(0, 0), a2, voffA);
;             PG8_WAIT_V(8); PG8_WAIT_L(0); PG8_BAR; PG8_MMA(1, 0, At, B0); PG8_MMA(1, 1, At, B1); PG8_BAR; PG8_SCHED;
.LBB0_766:
	s_add_i32 m0, s37, 0xc000
	s_nop 0
	global_load_lds_dwordx4 v152, s[24:25]
	s_add_i32 m0, s37, 0xe000
	s_nop 0
	global_load_lds_dwordx4 v154, s[24:25]
	ds_read_b128 v[120:123], v169
	ds_read_b128 v[124:127], v169 offset:1024
	ds_read_b128 v[136:139], v169 offset:2048
	ds_read_b128 v[140:143], v169 offset:3072
	ds_read_b128 v[160:163], v170
	ds_read_b128 v[172:175], v170 offset:1024
	ds_read_b128 v[176:179], v170 offset:2048
	ds_read_b128 v[180:183], v170 offset:3072
	ds_read_b128 v[184:187], v171
	ds_read_b128 v[188:191], v171 offset:1024
	ds_read_b128 v[192:195], v171 offset:2048
	ds_read_b128 v[196:199], v171 offset:3072
	ds_read_b128 v[200:203], v171 offset:4096
	ds_read_b128 v[204:207], v171 offset:5120
	ds_read_b128 v[208:211], v171 offset:6144
	ds_read_b128 v[212:215], v171 offset:7168
	s_add_u32 s26, s24, 0x100
	s_addc_u32 s27, s25, 0
	s_cmp_eq_u32 s56, 40
	s_cselect_b32 s31, s5, s27
	s_cselect_b32 s30, s4, s26
	s_cselect_b32 s29, s23, s55
	s_cselect_b32 s28, s22, s54
	s_waitcnt vmcnt(8)
	s_waitcnt lgkmcnt(0)
	s_barrier
	s_setprio 1
	s_waitcnt lgkmcnt(0)
	v_mfma_f32_16x16x32_bf16 v[132:135], v[120:123], v[184:187], v[132:135]
	v_mfma_f32_16x16x32_bf16 v[128:131], v[136:139], v[184:187], v[128:131]
	v_mfma_f32_16x16x32_bf16 v[108:111], v[120:123], v[192:195], v[108:111]
	v_mfma_f32_16x16x32_bf16 v[104:107], v[136:139], v[192:195], v[104:107]
	v_mfma_f32_16x16x32_bf16 v[92:95], v[120:123], v[200:203], v[92:95]
	v_mfma_f32_16x16x32_bf16 v[88:91], v[136:139], v[200:203], v[88:91]
	v_mfma_f32_16x16x32_bf16 v[76:79], v[120:123], v[208:211], v[76:79]
	v_mfma_f32_16x16x32_bf16 v[72:75], v[136:139], v[208:211], v[72:75]
	v_mfma_f32_16x16x32_bf16 v[132:135], v[124:127], v[188:191], v[132:135]
	v_mfma_f32_16x16x32_bf16 v[128:131], v[140:143], v[188:191], v[128:131]
	v_mfma_f32_16x16x32_bf16 v[108:111], v[124:127], v[196:199], v[108:111]
	v_mfma_f32_16x16x32_bf16 v[104:107], v[140:143], v[196:199], v[104:107]
	v_mfma_f32_16x16x32_bf16 v[92:95], v[124:127], v[204:207], v[92:95]
	v_mfma_f32_16x16x32_bf16 v[88:91], v[140:143], v[204:207], v[88:91]
	v_mfma_f32_16x16x32_bf16 v[76:79], v[124:127], v[212:215], v[76:79]
	v_mfma_f32_16x16x32_bf16 v[72:75], v[140:143], v[212:215], v[72:75]
	s_setprio 0
	s_setprio 1
	v_mfma_f32_16x16x32_bf16 v[116:119], v[160:163], v[184:187], v[116:119]
	v_mfma_f32_16x16x32_bf16 v[112:115], v[176:179], v[184:187], v[112:115]
	v_mfma_f32_16x16x32_bf16 v[100:103], v[160:163], v[192:195], v[100:103]
	v_mfma_f32_16x16x32_bf16 v[96:99], v[176:179], v[192:195], v[96:99]
	v_mfma_f32_16x16x32_bf16 v[84:87], v[160:163], v[200:203], v[84:87]
	v_mfma_f32_16x16x32_bf16 v[80:83], v[176:179], v[200:203], v[80:83]
	v_mfma_f32_16x16x32_bf16 v[68:71], v[160:163], v[208:211], v[68:71]
	v_mfma_f32_16x16x32_bf16 v[64:67], v[176:179], v[208:211], v[64:67]
	v_mfma_f32_16x16x32_bf16 v[116:119], v[172:175], v[188:191], v[116:119]
	v_mfma_f32_16x16x32_bf16 v[112:115], v[180:183], v[188:191], v[112:115]
	v_mfma_f32_16x16x32_bf16 v[100:103], v[172:175], v[196:199], v[100:103]
	v_mfma_f32_16x16x32_bf16 v[96:99], v[180:183], v[196:199], v[96:99]
	v_mfma_f32_16x16x32_bf16 v[84:87], v[172:175], v[204:207], v[84:87]
	v_mfma_f32_16x16x32_bf16 v[80:83], v[180:183], v[204:207], v[80:83]
	v_mfma_f32_16x16x32_bf16 v[68:71], v[172:175], v[212:215], v[68:71]
	v_mfma_f32_16x16x32_bf16 v[64:67], v[180:183], v[212:215], v[64:67]
	s_setprio 0
	s_barrier
	s_add_i32 s24, s48, s36
	s_mov_b32 m0, s24
	s_nop 0
	global_load_lds_dwordx4 v146, s[28:29]
	s_add_i32 m0, s24, 0x2000
	s_add_u32 s24, s28, 0xb0000
	s_addc_u32 s25, s29, 0
	s_add_i32 s57, s49, s36
	global_load_lds_dwordx4 v150, s[28:29]
	s_mov_b32 m0, s57
	s_nop 0
	global_load_lds_dwordx4 v146, s[24:25]
	s_add_i32 m0, s57, 0x2000
	s_nop 0
	global_load_lds_dwordx4 v150, s[24:25]
	s_mov_b32 m0, s37
	s_nop 0
	global_load_lds_dwordx4 v144, s[30:31]
	s_mov_b32 m0, s38
	s_nop 2
	global_load_lds_dwordx4 v148, s[30:31]
	ds_read_b128 v[184:187], v171 offset:16384
	ds_read_b128 v[188:191], v171 offset:17408
	ds_read_b128 v[192:195], v171 offset:18432
	ds_read_b128 v[196:199], v171 offset:19456
	ds_read_b128 v[200:203], v171 offset:20480
	ds_read_b128 v[204:207], v171 offset:21504
	ds_read_b128 v[208:211], v171 offset:22528
	ds_read_b128 v[212:215], v171 offset:23552
	s_waitcnt vmcnt(8)
	s_waitcnt lgkmcnt(0)
	s_barrier
	s_setprio 1
	s_waitcnt lgkmcnt(0)
	v_mfma_f32_16x16x32_bf16 v[60:63], v[120:123], v[184:187], v[60:63]
	v_mfma_f32_16x16x32_bf16 v[56:59], v[136:139], v[184:187], v[56:59]
	v_mfma_f32_16x16x32_bf16 v[44:47], v[120:123], v[192:195], v[44:47]
	v_mfma_f32_16x16x32_bf16 v[40:43], v[136:139], v[192:195], v[40:43]
	v_mfma_f32_16x16x32_bf16 v[28:31], v[120:123], v[200:203], v[28:31]
	v_mfma_f32_16x16x32_bf16 v[24:27], v[136:139], v[200:203], v[24:27]
	v_mfma_f32_16x16x32_bf16 v[12:15], v[120:123], v[208:211], v[12:15]
	v_mfma_f32_16x16x32_bf16 v[8:11], v[136:139], v[208:211], v[8:11]
	v_mfma_f32_16x16x32_bf16 v[60:63], v[124:127], v[188:191], v[60:63]
	v_mfma_f32_16x16x32_bf16 v[56:59], v[140:143], v[188:191], v[56:59]
	v_mfma_f32_16x16x32_bf16 v[44:47], v[124:127], v[196:199], v[44:47]
	v_mfma_f32_16x16x32_bf16 v[40:43], v[140:143], v[196:199], v[40:43]
	v_mfma_f32_16x16x32_bf16 v[28:31], v[124:127], v[204:207], v[28:31]
	v_mfma_f32_16x16x32_bf16 v[24:27], v[140:143], v[204:207], v[24:27]
	v_mfma_f32_16x16x32_bf16 v[12:15], v[124:127], v[212:215], v[12:15]
	v_mfma_f32_16x16x32_bf16 v[8:11], v[140:143], v[212:215], v[8:11]
	s_setprio 0
	s_setprio 1
	v_mfma_f32_16x16x32_bf16 v[52:55], v[160:163], v[184:187], v[52:55]
	v_mfma_f32_16x16x32_bf16 v[48:51], v[176:179], v[184:187], v[48:51]
	v_mfma_f32_16x16x32_bf16 v[36:39], v[160:163], v[192:195], v[36:39]
	v_mfma_f32_16x16x32_bf16 v[32:35], v[176:179], v[192:195], v[32:35]
	v_mfma_f32_16x16x32_bf16 v[20:23], v[160:163], v[200:203], v[20:23]
	v_mfma_f32_16x16x32_bf16 v[16:19], v[176:179], v[200:203], v[16:19]
	v_mfma_f32_16x16x32_bf16 v[4:7], v[160:163], v[208:211], v[4:7]
	v_mfma_f32_16x16x32_bf16 v[0:3], v[176:179], v[208:211], v[0:3]
	v_mfma_f32_16x16x32_bf16 v[52:55], v[172:175], v[188:191], v[52:55]
	v_mfma_f32_16x16x32_bf16 v[48:51], v[180:183], v[188:191], v[48:51]
	v_mfma_f32_16x16x32_bf16 v[36:39], v[172:175], v[196:199], v[36:39]
	v_mfma_f32_16x16x32_bf16 v[32:35], v[180:183], v[196:199], v[32:35]
	v_mfma_f32_16x16x32_bf16 v[20:23], v[172:175], v[204:207], v[20:23]
	v_mfma_f32_16x16x32_bf16 v[16:19], v[180:183], v[204:207], v[16:19]
	v_mfma_f32_16x16x32_bf16 v[4:7], v[172:175], v[212:215], v[4:7]
	v_mfma_f32_16x16x32_bf16 v[0:3], v[180:183], v[212:215], v[0:3]
	s_setprio 0
	s_barrier
; #define PG8_STAGE(bufoff, gbase, voff) do { _Pragma("unroll") for (int _i = 0; _i < 2; ++_i) \
;         __builtin_amdgcn_global_load_lds((const unsigned*)((const char*)(gbase) + (voff)[_i]), (LAS unsigned*)(lds + (bufoff) + ldsw + _i * 8192), 16, 0, 0); } while (0)
; #define PG8_LDA(dst, b, h) do { _Pragma("unroll") for (int m = 0; m < 4; ++m) _Pragma("unroll") for (int k = 0; k < 2; ++k) dst[m][k] = *(const LAS bf16x8*)(lds + PG8_SA(b, h) + aoff + m * 2048 + k * 1024); } while (0)
; #define PG8_LDB(dst, b, h) do { _Pragma("unroll") for (int n = 0; n < 2; ++n) _Pragma("unroll") for (int k = 0; k < 2; ++k) dst[n][k] = *(const LAS bf16x8*)(lds + PG8_SB(b, h) + boff + n * 2048 + k * 1024); } while (0)
; #define PG8_MMA(ai, bj, At, Bt) do { __builtin_amdgcn_s_setprio(1); _Pragma("unroll") for (int m = 0; m < 4; ++m) _Pragma("unroll") for (int n = 0; n < 2; ++n) _Pragma("unroll") for (int k = 0; k < 2; ++k) \
;         acc[ai][bj][m][n] = __builtin_amdgcn_mfma_f32_16x16x32_bf16(Bt[n][k], At[m][k], acc[ai][bj][m][n], 0, 0, 0); __builtin_amdgcn_s_setprio(0); } while (0)
; #define PG8_WAIT_V(n) asm volatile("s_waitcnt vmcnt(" #n ")" ::: "memory")
; #define PG8_WAIT_L(n) asm volatile("s_waitcnt lgkmcnt(" #n ")" ::: "memory")
; #define PG8_BAR __builtin_amdgcn_s_barrier()
; #define PG8_SCHED __builtin_amdgcn_sched_barrier(0)
; template <class Epi, class Sched, bool ALIGN_EPI, bool SP2>
; __device__ __forceinline__ void gemm_phase(LAS unsigned char* lds, const Gemm g, const Sched& S, const Epi& E) {
;     ...
;             PG8_LDB(B0, 1, 0); PG8_LDB(B1, 1, 1); PG8_SCHED; PG8_LDA(At, 1, 0); PG8_STAGE(PG8_SA(0, 1), a2 + hstep, voffA);
;             PG8_WAIT_V(8); PG8_WAIT_L(0); PG8_BAR; PG8_MMA(0, 0, At, B0); PG8_MMA(0, 1, At, B1); PG8_BAR; PG8_SCHED;
;             PG8_LDA(At, 1, 1); PG8_STAGE(PG8_SB(1, 0), b3, voffB); PG8_STAGE(PG8_SB(1, 1), b3 + hstep, voffB); PG8_STAGE(PG8_SA(1, 0), a3, voffA);
;             PG8_WAIT_V(8); PG8_WAIT_L(0); PG8_BAR; PG8_MMA(1, 0, At, B0); PG8_MMA(1, 1, At, B1); PG8_BAR; PG8_SCHED;
;     ...
;         }
;         if constexpr (ALIGN_EPI) { if (wr == 0) PG8_BAR; }
	s_add_i32 s57, 0, 0x18000
	s_add_i32 s58, 0, 0x1c000
	v_add_u32_e32 v140, s57, v167
	v_add_u32_e32 v180, s58, v167
	s_add_u32 s24, s30, 0xb0000
	s_addc_u32 s25, s31, 0
	s_mov_b32 m0, s39
	s_nop 0
	global_load_lds_dwordx4 v144, s[24:25]
	s_mov_b32 m0, s40
	s_nop 0
	global_load_lds_dwordx4 v148, s[24:25]
	ds_read_b128 v[120:123], v140
	ds_read_b128 v[124:127], v140 offset:1024
	ds_read_b128 v[136:139], v140 offset:2048
	ds_read_b128 v[140:143], v140 offset:3072
	ds_read_b128 v[160:163], v180
	ds_read_b128 v[172:175], v180 offset:1024
	ds_read_b128 v[176:179], v180 offset:2048
	ds_read_b128 v[180:183], v180 offset:3072
	ds_read_b128 v[184:187], v171 offset:32768
	ds_read_b128 v[188:191], v171 offset:33792
	ds_read_b128 v[192:195], v171 offset:34816
	ds_read_b128 v[196:199], v171 offset:35840
	ds_read_b128 v[200:203], v171 offset:36864
	ds_read_b128 v[204:207], v171 offset:37888
	ds_read_b128 v[208:211], v171 offset:38912
	ds_read_b128 v[212:215], v171 offset:39936
	s_waitcnt vmcnt(8)
	s_waitcnt lgkmcnt(0)
	s_barrier
	s_setprio 1
	s_waitcnt lgkmcnt(0)
	v_mfma_f32_16x16x32_bf16 v[132:135], v[120:123], v[184:187], v[132:135]
	v_mfma_f32_16x16x32_bf16 v[128:131], v[136:139], v[184:187], v[128:131]
	v_mfma_f32_16x16x32_bf16 v[108:111], v[120:123], v[192:195], v[108:111]
	v_mfma_f32_16x16x32_bf16 v[104:107], v[136:139], v[192:195], v[104:107]
	v_mfma_f32_16x16x32_bf16 v[92:95], v[120:123], v[200:203], v[92:95]
	v_mfma_f32_16x16x32_bf16 v[88:91], v[136:139], v[200:203], v[88:91]
	v_mfma_f32_16x16x32_bf16 v[76:79], v[120:123], v[208:211], v[76:79]
	v_mfma_f32_16x16x32_bf16 v[72:75], v[136:139], v[208:211], v[72:75]
	v_mfma_f32_16x16x32_bf16 v[132:135], v[124:127], v[188:191], v[132:135]
	v_mfma_f32_16x16x32_bf16 v[128:131], v[140:143], v[188:191], v[128:131]
	v_mfma_f32_16x16x32_bf16 v[108:111], v[124:127], v[196:199], v[108:111]
	v_mfma_f32_16x16x32_bf16 v[104:107], v[140:143], v[196:199], v[104:107]
	v_mfma_f32_16x16x32_bf16 v[92:95], v[124:127], v[204:207], v[92:95]
	v_mfma_f32_16x16x32_bf16 v[88:91], v[140:143], v[204:207], v[88:91]
	v_mfma_f32_16x16x32_bf16 v[76:79], v[124:127], v[212:215], v[76:79]
	v_mfma_f32_16x16x32_bf16 v[72:75], v[140:143], v[212:215], v[72:75]
	s_setprio 0
	s_setprio 1
	v_mfma_f32_16x16x32_bf16 v[116:119], v[160:163], v[184:187], v[116:119]
	v_mfma_f32_16x16x32_bf16 v[112:115], v[176:179], v[184:187], v[112:115]
	v_mfma_f32_16x16x32_bf16 v[100:103], v[160:163], v[192:195], v[100:103]
	v_mfma_f32_16x16x32_bf16 v[96:99], v[176:179], v[192:195], v[96:99]
	v_mfma_f32_16x16x32_bf16 v[84:87], v[160:163], v[200:203], v[84:87]
	v_mfma_f32_16x16x32_bf16 v[80:83], v[176:179], v[200:203], v[80:83]
	v_mfma_f32_16x16x32_bf16 v[68:71], v[160:163], v[208:211], v[68:71]
	v_mfma_f32_16x16x32_bf16 v[64:67], v[176:179], v[208:211], v[64:67]
	v_mfma_f32_16x16x32_bf16 v[116:119], v[172:175], v[188:191], v[116:119]
	v_mfma_f32_16x16x32_bf16 v[112:115], v[180:183], v[188:191], v[112:115]
	v_mfma_f32_16x16x32_bf16 v[100:103], v[172:175], v[196:199], v[100:103]
	v_mfma_f32_16x16x32_bf16 v[96:99], v[180:183], v[196:199], v[96:99]
	v_mfma_f32_16x16x32_bf16 v[84:87], v[172:175], v[204:207], v[84:87]
	v_mfma_f32_16x16x32_bf16 v[80:83], v[180:183], v[204:207], v[80:83]
	v_mfma_f32_16x16x32_bf16 v[68:71], v[172:175], v[212:215], v[68:71]
	v_mfma_f32_16x16x32_bf16 v[64:67], v[180:183], v[212:215], v[64:67]
	s_setprio 0
	s_barrier
	s_add_u32 s100, s24, 0xfff50080
	s_addc_u32 s101, s25, -1
	s_add_u32 s98, s28, 0x80
	s_addc_u32 s99, s29, 0
	s_add_i32 s24, s57, s36
	s_mov_b32 m0, s24
	s_nop 0
	global_load_lds_dwordx4 v146, s[98:99]
	s_add_i32 m0, s24, 0x2000
	s_add_u32 s24, s28, 0xb0080
	s_addc_u32 s25, s29, 0
	s_add_i32 s28, s58, s36
	global_load_lds_dwordx4 v150, s[98:99]
	s_mov_b32 m0, s28
	s_nop 0
	global_load_lds_dwordx4 v146, s[24:25]
	s_add_i32 m0, s28, 0x2000
	s_nop 0
	global_load_lds_dwordx4 v150, s[24:25]
	s_mov_b32 m0, s45
	s_nop 0
	global_load_lds_dwordx4 v144, s[100:101]
	s_mov_b32 m0, s46
	s_nop 0
	global_load_lds_dwordx4 v148, s[100:101]
	ds_read_b128 v[184:187], v171 offset:49152
	ds_read_b128 v[188:191], v171 offset:50176
	ds_read_b128 v[192:195], v171 offset:51200
	ds_read_b128 v[196:199], v171 offset:52224
	ds_read_b128 v[200:203], v171 offset:53248
	ds_read_b128 v[204:207], v171 offset:54272
	ds_read_b128 v[208:211], v171 offset:55296
	ds_read_b128 v[212:215], v171 offset:56320
	s_waitcnt vmcnt(8)
	s_waitcnt lgkmcnt(0)
	s_barrier
	s_setprio 1
	s_waitcnt lgkmcnt(0)
	v_mfma_f32_16x16x32_bf16 v[60:63], v[120:123], v[184:187], v[60:63]
	v_mfma_f32_16x16x32_bf16 v[56:59], v[136:139], v[184:187], v[56:59]
	v_mfma_f32_16x16x32_bf16 v[44:47], v[120:123], v[192:195], v[44:47]
	v_mfma_f32_16x16x32_bf16 v[40:43], v[136:139], v[192:195], v[40:43]
	v_mfma_f32_16x16x32_bf16 v[28:31], v[120:123], v[200:203], v[28:31]
	v_mfma_f32_16x16x32_bf16 v[24:27], v[136:139], v[200:203], v[24:27]
	v_mfma_f32_16x16x32_bf16 v[12:15], v[120:123], v[208:211], v[12:15]
	v_mfma_f32_16x16x32_bf16 v[8:11], v[136:139], v[208:211], v[8:11]
	v_mfma_f32_16x16x32_bf16 v[60:63], v[124:127], v[188:191], v[60:63]
	v_mfma_f32_16x16x32_bf16 v[56:59], v[140:143], v[188:191], v[56:59]
	v_mfma_f32_16x16x32_bf16 v[44:47], v[124:127], v[196:199], v[44:47]
	v_mfma_f32_16x16x32_bf16 v[40:43], v[140:143], v[196:199], v[40:43]
	v_mfma_f32_16x16x32_bf16 v[28:31], v[124:127], v[204:207], v[28:31]
	v_mfma_f32_16x16x32_bf16 v[24:27], v[140:143], v[204:207], v[24:27]
	v_mfma_f32_16x16x32_bf16 v[12:15], v[124:127], v[212:215], v[12:15]
	v_mfma_f32_16x16x32_bf16 v[8:11], v[140:143], v[212:215], v[8:11]
	s_setprio 0
	s_setprio 1
	v_mfma_f32_16x16x32_bf16 v[52:55], v[160:163], v[184:187], v[52:55]
	v_mfma_f32_16x16x32_bf16 v[48:51], v[176:179], v[184:187], v[48:51]
	v_mfma_f32_16x16x32_bf16 v[36:39], v[160:163], v[192:195], v[36:39]
	v_mfma_f32_16x16x32_bf16 v[32:35], v[176:179], v[192:195], v[32:35]
	v_mfma_f32_16x16x32_bf16 v[20:23], v[160:163], v[200:203], v[20:23]
	v_mfma_f32_16x16x32_bf16 v[16:19], v[176:179], v[200:203], v[16:19]
	v_mfma_f32_16x16x32_bf16 v[4:7], v[160:163], v[208:211], v[4:7]
	v_mfma_f32_16x16x32_bf16 v[0:3], v[176:179], v[208:211], v[0:3]
	v_mfma_f32_16x16x32_bf16 v[52:55], v[172:175], v[188:191], v[52:55]
	v_mfma_f32_16x16x32_bf16 v[48:51], v[180:183], v[188:191], v[48:51]
	v_mfma_f32_16x16x32_bf16 v[36:39], v[172:175], v[196:199], v[36:39]
	v_mfma_f32_16x16x32_bf16 v[32:35], v[180:183], v[196:199], v[32:35]
	v_mfma_f32_16x16x32_bf16 v[20:23], v[172:175], v[204:207], v[20:23]
	v_mfma_f32_16x16x32_bf16 v[16:19], v[180:183], v[204:207], v[16:19]
	v_mfma_f32_16x16x32_bf16 v[4:7], v[172:175], v[212:215], v[4:7]
	v_mfma_f32_16x16x32_bf16 v[0:3], v[180:183], v[212:215], v[0:3]
	s_setprio 0
	s_barrier
	s_add_i32 s56, s56, 2
	s_add_u32 s54, s54, 0x100
	s_addc_u32 s55, s55, 0
	s_cmp_gt_u32 s56, 41
	s_mov_b64 s[24:25], s[26:27]
	s_cbranch_scc0 .LBB0_766
	s_and_b64 vcc, exec, s[12:13]
	s_cbranch_vccz .LBB0_769
	s_barrier
